# NSA loops: 77 v_pk_mul_f32 (broadcast scale) beside MFMAs split into scalar v_mul_f32 pairs (bit-identical), on top of the phase H warm-up version
# baseline (speedup 1.0000x reference)
; DI void nsa_item(int wv0, PP p, int item, unsigned char* smem) {
;     ...
; #pragma unroll
;     for (int qt = 0; qt < 2; ++qt) {
;       const float gt = NGb[ngoff + qt * 3 + 0];
; #pragma unroll
;       for (int dt = 0; dt < 4; ++dt) {
;         float4 o = make_float4(O[qt][dt][0] * gt, O[qt][dt][1] * gt, O[qt][dt][2] * gt, O[qt][dt][3] * gt);
;         *(float4*)(ACCb + (aoff + qt * 64 + 16 * dt)) = o;
;       }
;     }
;   }
;   __syncthreads();
;   u64 mlo = 0, mhi = 0, wlo = 0, whi = 0;
;   if (i < 16) {
;     mlo = (1ull << (i + 1)) - 1ull;
;     wlo = mlo;
;   } else {
;     const bool v0 = lane <= i, v1 = (lane + 64) <= i;
;     const bool f0 = (lane == 0) || (lane == i) || (lane == i - 1);
;     const bool f1 = (lane + 64 == i) || (lane + 64 == i - 1);
;     const u64 ltm = (1ull << lane) - 1ull;
.LBB0_813:
	s_mul_i32 s2, s40, 12
	v_readlane_b32 s3, v247, 49
	s_add_i32 s2, s2, s3
	v_mov_b32_e32 v2, s2
	v_mad_u64_u32 v[142:143], s[2:3], v74, 24, v[2:3]
	v_mov_b32_e32 v143, v1
	v_lshl_add_u64 v[2:3], v[142:143], 2, s[94:95]
	global_load_dword v16, v[2:3], off
	v_readlane_b32 s2, v247, 5
	v_readlane_b32 s3, v247, 6
	s_load_dwordx2 s[2:3], s[2:3], 0xc0
	v_or_b32_e32 v138, v72, v153
	v_mov_b32_e32 v139, v1
	v_mov_b32_e32 v3, v1
	v_add_u32_e32 v2, 3, v142
	s_waitcnt lgkmcnt(0)
	v_lshl_add_u64 v[140:141], v[138:139], 2, s[2:3]
	s_waitcnt vmcnt(1)
	v_lshl_add_u64 v[34:35], v[2:3], 2, s[94:95]
	global_load_dword v200, v[34:35], off
	s_mov_b64 s[2:3], -1
	s_cmpk_lt_i32 s88, 0x70
	v_cmp_eq_u32_e32 vcc, 0, v71
	s_waitcnt vmcnt(0)
	v_mul_f32_e32 v2, v54, v16
	v_mul_f32_e32 v3, v55, v16
	v_mul_f32_e32 v4, v56, v16
	v_mul_f32_e32 v5, v57, v16
	v_mul_f32_e32 v6, v50, v16
	v_mul_f32_e32 v7, v51, v16
	v_mul_f32_e32 v8, v52, v16
	v_mul_f32_e32 v9, v53, v16
	v_mul_f32_e32 v10, v46, v16
	v_mul_f32_e32 v11, v47, v16
	v_mul_f32_e32 v12, v48, v16
	v_mul_f32_e32 v13, v49, v16
	v_mul_f32_e32 v14, v42, v16
	v_mul_f32_e32 v15, v43, v16
	v_mul_f32_e32 v17, v45, v16
	v_mul_f32_e32 v16, v44, v16
	v_mov_b64_e32 v[218:219], v[2:3]
	v_mov_b64_e32 v[220:221], v[4:5]
	v_mov_b64_e32 v[222:223], v[6:7]
	v_mov_b64_e32 v[224:225], v[8:9]
	v_mov_b64_e32 v[226:227], v[10:11]
	v_mov_b64_e32 v[228:229], v[12:13]
	v_mov_b64_e32 v[230:231], v[14:15]
	v_mov_b64_e32 v[232:233], v[16:17]
	v_mul_f32_e32 v2, v30, v200
	v_mul_f32_e32 v3, v31, v200
	v_mul_f32_e32 v4, v32, v200
	v_mul_f32_e32 v5, v33, v200
	v_mul_f32_e32 v6, v26, v200
	v_mul_f32_e32 v7, v27, v200
	v_mul_f32_e32 v8, v28, v200
	v_mul_f32_e32 v9, v29, v200
	v_mul_f32_e32 v10, v22, v200
	v_mul_f32_e32 v11, v23, v200
	v_mul_f32_e32 v12, v24, v200
	v_mul_f32_e32 v13, v25, v200
	v_mul_f32_e32 v14, v18, v200
	v_mul_f32_e32 v15, v19, v200
	v_mul_f32_e32 v16, v20, v200
	v_mul_f32_e32 v17, v21, v200
	v_mov_b64_e32 v[234:235], v[2:3]
	v_mov_b64_e32 v[236:237], v[4:5]
	v_mov_b64_e32 v[238:239], v[6:7]
	v_mov_b64_e32 v[240:241], v[8:9]
	v_mov_b64_e32 v[242:243], v[10:11]
	v_mov_b64_e32 v[244:245], v[12:13]
	v_mov_b64_e32 v[248:249], v[14:15]
	v_mov_b64_e32 v[250:251], v[16:17]
	v_lshlrev_b32_e32 v206, 1, v0
	global_load_dword v202, v206, s[86:87]
	global_load_dword v203, v206, s[86:87] offset:128
	s_lshl_b32 s32, s84, 20
	v_readlane_b32 s4, v247, 59
	v_readlane_b32 s5, v247, 60
	s_nop 1
	s_add_u32 s4, s4, s32
	s_addc_u32 s5, s5, 0
	v_lshl_or_b32 v207, v70, 14, v68
	s_nop 3
	global_load_dword v204, v152, s[4:5]
	v_readlane_b32 s4, v247, 61
	v_readlane_b32 s5, v247, 62
	s_nop 1
	s_add_u32 s4, s4, s32
	s_addc_u32 s5, s5, 0
	s_nop 4
	global_load_dword v205, v207, s[4:5]
	s_cmpk_lt_i32 s88, 0x70
	s_barrier
	s_cbranch_scc0 .LBB0_820
	v_cmp_eq_u32_e64 s[10:11], s33, v71
	s_sub_i32 s14, 0x7e, s88
	s_or_b64 s[12:13], vcc, s[10:11]
	v_cmp_eq_u32_e64 s[10:11], s14, v71
	v_or_b32_e32 v2, 64, v71
	s_or_b64 s[10:11], s[12:13], s[10:11]
	v_cndmask_b32_e64 v4, 0, v149, s[10:11]
	v_cmp_eq_u32_e64 s[10:11], s33, v2
	v_cmp_eq_u32_e64 s[12:13], s14, v2
	s_or_b64 s[10:11], s[10:11], s[12:13]
	v_cmp_lt_i32_e64 s[6:7], s33, v2
	v_cmp_ge_i32_e64 s[8:9], s33, v2
	v_cndmask_b32_e64 v5, 0, v149, s[10:11]
	v_lshlrev_b64 v[2:3], v71, -1
	v_readlane_b32 s10, v246, 7
	v_cmp_lt_i32_e64 s[2:3], s33, v71
	v_cmp_ge_i32_e64 s[4:5], s33, v71
	v_not_b32_e32 v3, v3
	v_not_b32_e32 v2, v2
	v_lshl_add_u32 v6, v71, 2, s10
	s_mov_b64 s[20:21], 0
	s_mov_b32 s24, 8
	v_readlane_b32 s25, v246, 6
	s_mov_b64 s[22:23], 0
	s_branch .LBB0_816

; template <int MODE, bool MASKED, class MaskF>
; DI void flash_tile(const u16* sK, const u16* sV, const bf16x8 (&qf)[2][2], f32x4 (&O)[2][4], float (&m)[2], float (&l)[2],
;                    float (&ps)[4][4], MaskF ok, bool sel, int lane) {
;     ...
;   for (int qt = 0; qt < 2; ++qt) {
;     f32x4 s[4];
;     const float sinit = (MODE == 3) ? ((MASKED || sel) ? m[qt] : -1e30f) : 0.f;
; #pragma unroll
;     for (int kt = 0; kt < 4; ++kt) {
;       s[kt] = f32x4{sinit, sinit, sinit, sinit};
; #pragma unroll
;       for (int ks = 0; ks < 2; ++ks) s[kt] = mfma16(kf[kt][ks], qf[qt][ks], s[kt]);
;     }
;     float pr[4][4];
;     if (MODE == 3) {
;       float rs = 0.f;
; #pragma unroll
;       for (int kt = 0; kt < 4; ++kt)
; #pragma unroll
;         for (int i = 0; i < 4; ++i) {
;           float pv = __builtin_amdgcn_exp2f(s[kt][i]);
;           if (MASKED) pv = ok(kt, i) ? pv : 0.f;
;           pr[kt][i] = pv;
;           rs += pv;
;         }
;       l[qt] += rs;
;     } else {
;     float mx = -1e30f;
; #pragma unroll
;     for (int kt = 0; kt < 4; ++kt)
; #pragma unroll
;       for (int i = 0; i < 4; ++i) {
;         if (MASKED) s[kt][i] = ok(kt, i) ? s[kt][i] : -1e30f;
;         mx = fmaxf(mx, s[kt][i]);
;       }
;     if (!MASKED) mx = sel ? mx : -1e30f;
;     if (MODE == 1) {
;       const float mm = m[qt], il = l[qt];
; #pragma unroll
;       for (int kt = 0; kt < 4; ++kt)
; #pragma unroll
;         for (int i = 0; i < 4; ++i) {
;           const float pv = (s[kt][i] > -1e29f) ? __builtin_amdgcn_exp2f(s[kt][i] - mm) * il : 0.f;
;           pr[kt][i] = pv;
;           ps[kt][i] += pv;
;         }
;     } else {
;       mx = fmaxf(mx, __shfl_xor(mx, 16));
;       mx = fmaxf(mx, __shfl_xor(mx, 32));
;       const float mnew = fmaxf(m[qt], mx);
;       const float alpha = __builtin_amdgcn_exp2f(m[qt] - mnew);
;       m[qt] = mnew;
;       float rs = 0.f;
;       if (MASKED) {
; #pragma unroll
;         for (int kt = 0; kt < 4; ++kt)
; #pragma unroll
;           for (int i = 0; i < 4; ++i) {
;             const float pv = (s[kt][i] > -1e29f) ? __builtin_amdgcn_exp2f(s[kt][i] - mnew) : 0.f;
;             pr[kt][i] = pv;
;             rs += pv;
;           }
;       } else {
;         const float me = sel ? mnew : 1e30f;
; #pragma unroll
;         for (int kt = 0; kt < 4; ++kt)
; #pragma unroll
;           for (int i = 0; i < 4; ++i) {
.LBB0_841:
	v_sub_co_u32_e64 v2, s[36:37], s38, 64
	v_lshrrev_b64 v[66:67], s38, v[130:131]
	v_lshrrev_b64 v[68:69], v2, v[134:135]
	v_cndmask_b32_e64 v0, v68, v66, s[36:37]
	v_and_b32_e32 v0, 1, v0
	v_cmp_eq_u64_e32 vcc, 0, v[0:1]
	s_mov_b32 s81, s40
	s_cbranch_vccnz .LBB0_847
	v_lshrrev_b64 v[66:67], s38, v[20:21]
	v_lshrrev_b64 v[2:3], v2, v[22:23]
	v_cndmask_b32_e64 v0, v2, v66, s[36:37]
	s_mul_i32 s39, s80, 0x4800
	v_and_b32_e32 v0, 1, v0
	v_cmp_eq_u64_e64 s[36:37], 0, v[0:1]
	v_add_u32_e32 v0, s39, v165
	v_lshl_add_u32 v2, v28, 1, v0
	ds_read_b128 v[94:97], v2
	ds_read_b128 v[90:93], v2 offset:64
	ds_read_b128 v[86:89], v2 offset:2304
	ds_read_b128 v[82:85], v2 offset:2368
	ds_read_b128 v[78:81], v2 offset:4608
	ds_read_b128 v[74:77], v2 offset:4672
	v_lshl_add_u32 v0, v164, 1, v0
	ds_read_b128 v[70:73], v0
	ds_read_b128 v[66:69], v0 offset:64
	s_add_i32 s74, s39, 32
	s_cmp_lg_u32 s38, s33
	s_mov_b64 s[38:39], -1
	v_lshlrev_b32_e32 v3, 1, v28
	v_lshlrev_b32_e32 v0, 1, v164
	s_cbranch_scc0 .LBB0_844
	s_waitcnt lgkmcnt(7)
	v_mfma_f32_16x16x32_bf16 v[98:101], v[94:97], v[4:7], 0
	s_mov_b64 s[38:39], 0
	s_waitcnt lgkmcnt(5)
	v_mfma_f32_16x16x32_bf16 v[102:105], v[86:89], v[4:7], 0
	v_mfma_f32_16x16x32_bf16 v[98:101], v[90:93], v[8:11], v[98:101]
	s_waitcnt lgkmcnt(3)
	v_mfma_f32_16x16x32_bf16 v[106:109], v[78:81], v[4:7], 0
	v_mfma_f32_16x16x32_bf16 v[102:105], v[82:85], v[8:11], v[102:105]
	s_nop 4
	v_max3_f32 v2, v98, s1, v99
	v_max3_f32 v2, v2, v100, v101
	s_waitcnt lgkmcnt(1)
	v_mfma_f32_16x16x32_bf16 v[110:113], v[70:73], v[4:7], 0
	v_mfma_f32_16x16x32_bf16 v[106:109], v[74:77], v[8:11], v[106:109]
	v_max3_f32 v2, v2, v102, v103
	v_max3_f32 v2, v2, v104, v105
	s_waitcnt lgkmcnt(0)
	v_mfma_f32_16x16x32_bf16 v[110:113], v[66:69], v[8:11], v[110:113]
	v_mfma_f32_16x16x32_bf16 v[174:177], v[70:73], v[12:15], 0
	s_nop 2
	v_max3_f32 v2, v2, v106, v107
	v_max3_f32 v2, v2, v108, v109
	s_nop 1
	v_max3_f32 v2, v2, v110, v111
	v_max3_f32 v2, v2, v112, v113
	v_cndmask_b32_e64 v2, v2, v148, s[36:37]
	ds_bpermute_b32 v114, v144, v2
	v_mfma_f32_16x16x32_bf16 v[174:177], v[66:69], v[16:19], v[174:177]
	s_waitcnt lgkmcnt(0)
	v_max_f32_e32 v114, v114, v114
	v_max_f32_e32 v2, v2, v114
	ds_bpermute_b32 v114, v145, v2
	s_waitcnt lgkmcnt(0)
	v_max3_f32 v2, v167, v2, v114
	v_cndmask_b32_e64 v115, v2, v150, s[36:37]
	v_sub_f32_e32 v98, v98, v115
	v_exp_f32_e32 v122, v98
	v_sub_f32_e32 v99, v99, v115
	v_exp_f32_e32 v99, v99
	v_sub_f32_e32 v100, v100, v115
	v_exp_f32_e32 v100, v100
	v_sub_f32_e32 v101, v101, v115
	v_exp_f32_e32 v101, v101
	v_sub_f32_e32 v102, v102, v115
	v_add_f32_e32 v98, 0, v122
	v_exp_f32_e32 v123, v102
	v_sub_f32_e32 v102, v103, v115
	v_add_f32_e32 v98, v99, v98
	v_exp_f32_e32 v124, v102
	v_sub_f32_e32 v102, v104, v115
	v_add_f32_e32 v98, v100, v98
	v_exp_f32_e32 v125, v102
	v_sub_f32_e32 v102, v105, v115
	v_add_f32_e32 v98, v101, v98
	v_exp_f32_e32 v126, v102
	v_sub_f32_e32 v102, v106, v115
	v_add_f32_e32 v98, v123, v98
	v_exp_f32_e32 v127, v102
	v_sub_f32_e32 v102, v107, v115
	v_add_f32_e32 v98, v124, v98
	v_exp_f32_e32 v128, v102
	v_sub_f32_e32 v102, v108, v115
	v_add_f32_e32 v98, v125, v98
	v_exp_f32_e32 v129, v102
	v_sub_f32_e32 v102, v109, v115
	v_add_f32_e32 v98, v126, v98
	v_exp_f32_e32 v169, v102
	v_sub_f32_e32 v102, v110, v115
	v_add_f32_e32 v98, v127, v98
	v_exp_f32_e32 v170, v102
	v_sub_f32_e32 v102, v111, v115
	v_add_f32_e32 v98, v128, v98
	v_exp_f32_e32 v171, v102
	v_sub_f32_e32 v102, v112, v115
	v_add_f32_e32 v98, v129, v98
	v_exp_f32_e32 v172, v102
	v_sub_f32_e32 v102, v113, v115
	v_add_f32_e32 v98, v169, v98
	v_exp_f32_e32 v173, v102
	v_add_f32_e32 v98, v170, v98
	v_add_f32_e32 v98, v171, v98
	v_sub_f32_e32 v114, v167, v2
	v_add_f32_e32 v98, v172, v98
	v_add_f32_e32 v168, v173, v98
	v_exp_f32_e32 v98, v114
	v_cvt_pk_bf16_f32 v106, v122, v99
	v_cvt_pk_bf16_f32 v108, v123, v124
	v_cvt_pk_bf16_f32 v109, v125, v126
	v_mfma_f32_16x16x32_bf16 v[122:125], v[94:97], v[12:15], 0
	v_fmac_f32_e32 v168, v163, v98
	v_mul_f32_e32 v120, v60, v98
	v_mul_f32_e32 v121, v61, v98
	v_mul_f32_e32 v118, v58, v98
	v_mul_f32_e32 v119, v59, v98
	v_mul_f32_e32 v116, v56, v98
	v_mul_f32_e32 v117, v57, v98
	v_mul_f32_e32 v114, v54, v98
	v_mul_f32_e32 v115, v55, v98
	v_mul_f32_e32 v112, v52, v98
	v_mul_f32_e32 v113, v53, v98
	v_mul_f32_e32 v110, v50, v98
	v_mul_f32_e32 v111, v51, v98
	v_mul_f32_e32 v104, v48, v98
	v_mul_f32_e32 v105, v49, v98
	v_mul_f32_e32 v102, v46, v98
	v_mul_f32_e32 v103, v47, v98
	v_cvt_pk_bf16_f32 v98, v127, v128
	v_cvt_pk_bf16_f32 v99, v129, v169
	v_mfma_f32_16x16x32_bf16 v[126:129], v[86:89], v[12:15], 0
	v_cvt_pk_bf16_f32 v107, v100, v101
	v_cvt_pk_bf16_f32 v100, v170, v171
	v_cvt_pk_bf16_f32 v101, v172, v173
	v_mfma_f32_16x16x32_bf16 v[122:125], v[90:93], v[16:19], v[122:125]
	v_mfma_f32_16x16x32_bf16 v[170:173], v[78:81], v[12:15], 0
	v_mfma_f32_16x16x32_bf16 v[126:129], v[82:85], v[16:19], v[126:129]
	s_nop 5
	v_max3_f32 v169, v122, s1, v123
	v_max3_f32 v169, v169, v124, v125
	v_mfma_f32_16x16x32_bf16 v[170:173], v[74:77], v[16:19], v[170:173]
	v_max3_f32 v169, v169, v126, v127
	v_max3_f32 v169, v169, v128, v129
	s_nop 5
	v_max3_f32 v169, v169, v170, v171
	v_max3_f32 v169, v169, v172, v173
	v_max3_f32 v169, v169, v174, v175
	v_max3_f32 v169, v169, v176, v177
	v_cndmask_b32_e64 v169, v169, v148, s[36:37]
	ds_bpermute_b32 v178, v144, v169
	s_waitcnt lgkmcnt(0)
	v_max_f32_e32 v178, v178, v178
	v_max_f32_e32 v169, v169, v178
	ds_bpermute_b32 v178, v145, v169
	s_waitcnt lgkmcnt(0)
; DI f32x4 mfma16(bf16x8 a, bf16x8 b, f32x4 c) { return __builtin_amdgcn_mfma_f32_16x16x32_bf16(a, b, c, 0, 0, 0); }
; template <int MODE, bool MASKED, class MaskF>
; DI void flash_tile(const u16* sK, const u16* sV, const bf16x8 (&qf)[2][2], f32x4 (&O)[2][4], float (&m)[2], float (&l)[2],
;                    float (&ps)[4][4], MaskF ok, bool sel, int lane) {
;     ...
;       mx = fmaxf(mx, __shfl_xor(mx, 16));
;       mx = fmaxf(mx, __shfl_xor(mx, 32));
;       const float mnew = fmaxf(m[qt], mx);
;       const float alpha = __builtin_amdgcn_exp2f(m[qt] - mnew);
;       m[qt] = mnew;
;       float rs = 0.f;
;       if (MASKED) {
; #pragma unroll
;         for (int kt = 0; kt < 4; ++kt)
; #pragma unroll
;           for (int i = 0; i < 4; ++i) {
;             const float pv = (s[kt][i] > -1e29f) ? __builtin_amdgcn_exp2f(s[kt][i] - mnew) : 0.f;
;             pr[kt][i] = pv;
;             rs += pv;
;           }
;       } else {
;         const float me = sel ? mnew : 1e30f;
; #pragma unroll
;         for (int kt = 0; kt < 4; ++kt)
; #pragma unroll
;           for (int i = 0; i < 4; ++i) {
;             const float pv = __builtin_amdgcn_exp2f(s[kt][i] - me);
;             pr[kt][i] = pv;
;             rs += pv;
;           }
;       }
;       l[qt] = l[qt] * alpha + rs;
;       if (MODE == 2) {
; #pragma unroll
;         for (int dt = 0; dt < 4; ++dt) O[qt][dt] *= alpha;
;       }
;     }
;     }
;     if (MODE != 0) {
; #pragma unroll
;       for (int ks2 = 0; ks2 < 2; ++ks2) {
;         pf[qt][ks2].u[0] = pk2(pr[2 * ks2][0], pr[2 * ks2][1]);
;         pf[qt][ks2].u[1] = pk2(pr[2 * ks2][2], pr[2 * ks2][3]);
;         pf[qt][ks2].u[2] = pk2(pr[2 * ks2 + 1][0], pr[2 * ks2 + 1][1]);
;         pf[qt][ks2].u[3] = pk2(pr[2 * ks2 + 1][2], pr[2 * ks2 + 1][3]);
;       }
;     }
;   }
;   if (MODE != 0) {
; #pragma unroll
;     for (int ks2 = 0; ks2 < 2; ++ks2) {
; #pragma unroll
;       for (int dt = 0; dt < 4; ++dt) {
;         union { uint2 h[2]; bf16x8 v; } vf;
;         vf.h[0] = *(const uint2*)(sV + (16 * dt + l15) * 72 + 32 * ks2 + 4 * lg);
;         vf.h[1] = *(const uint2*)(sV + (16 * dt + l15) * 72 + 32 * ks2 + 16 + 4 * lg);
;         O[0][dt] = mfma16(vf.v, pf[0][ks2].v, O[0][dt]);
;         O[1][dt] = mfma16(vf.v, pf[1][ks2].v, O[1][dt]);
;       }
;     }
	v_max3_f32 v169, v166, v169, v178
	v_cndmask_b32_e64 v179, v169, v150, s[36:37]
	v_sub_f32_e32 v122, v122, v179
	v_exp_f32_e32 v184, v122
	v_sub_f32_e32 v123, v123, v179
	v_exp_f32_e32 v123, v123
	v_sub_f32_e32 v124, v124, v179
	v_exp_f32_e32 v124, v124
	v_sub_f32_e32 v125, v125, v179
	v_exp_f32_e32 v125, v125
	v_sub_f32_e32 v126, v126, v179
	v_add_f32_e32 v122, 0, v184
	v_exp_f32_e32 v186, v126
	v_sub_f32_e32 v126, v127, v179
	v_add_f32_e32 v122, v123, v122
	v_exp_f32_e32 v187, v126
	v_sub_f32_e32 v126, v128, v179
	v_add_f32_e32 v122, v124, v122
	v_exp_f32_e32 v188, v126
	v_sub_f32_e32 v126, v129, v179
	v_add_f32_e32 v122, v125, v122
	v_exp_f32_e32 v189, v126
	v_sub_f32_e32 v126, v170, v179
	v_add_f32_e32 v122, v186, v122
	v_exp_f32_e32 v190, v126
	v_sub_f32_e32 v126, v171, v179
	v_add_f32_e32 v122, v187, v122
	v_exp_f32_e32 v171, v126
	v_sub_f32_e32 v126, v172, v179
	v_add_f32_e32 v122, v188, v122
	v_exp_f32_e32 v191, v126
	v_sub_f32_e32 v126, v173, v179
	v_add_f32_e32 v122, v189, v122
	v_exp_f32_e32 v192, v126
	v_sub_f32_e32 v126, v174, v179
	v_add_f32_e32 v122, v190, v122
	v_exp_f32_e32 v193, v126
	v_sub_f32_e32 v126, v175, v179
	v_add_f32_e32 v122, v171, v122
	v_exp_f32_e32 v194, v126
	v_sub_f32_e32 v126, v176, v179
	v_add_f32_e32 v122, v191, v122
	v_exp_f32_e32 v195, v126
	v_sub_f32_e32 v126, v177, v179
	v_add_f32_e32 v122, v192, v122
	v_exp_f32_e32 v196, v126
	v_add_f32_e32 v122, v193, v122
	v_add_f32_e32 v122, v194, v122
	v_sub_f32_e32 v178, v166, v169
	v_add_f32_e32 v122, v195, v122
	v_add_f32_e32 v170, v196, v122
	v_exp_f32_e32 v122, v178
	v_cvt_pk_bf16_f32 v184, v184, v123
	v_cvt_pk_bf16_f32 v185, v124, v125
	v_cvt_pk_bf16_f32 v125, v195, v196
	v_fmac_f32_e32 v170, v162, v122
	v_mul_f32_e32 v128, v44, v122
	v_mul_f32_e32 v129, v45, v122
	v_mul_f32_e32 v126, v42, v122
	v_mul_f32_e32 v127, v43, v122
	v_mul_f32_e32 v174, v40, v122
	v_mul_f32_e32 v175, v41, v122
	v_mul_f32_e32 v172, v38, v122
	v_mul_f32_e32 v173, v39, v122
	v_mul_f32_e32 v178, v36, v122
	v_mul_f32_e32 v179, v37, v122
	v_mul_f32_e32 v176, v34, v122
	v_mul_f32_e32 v177, v35, v122
	v_mul_f32_e32 v182, v32, v122
	v_mul_f32_e32 v183, v33, v122
	v_mul_f32_e32 v180, v30, v122
	v_mul_f32_e32 v181, v31, v122
	v_cvt_pk_bf16_f32 v122, v190, v171
	v_lshlrev_b32_e32 v171, 1, v153
	v_cvt_pk_bf16_f32 v123, v191, v192
	v_add3_u32 v192, s74, v3, v171
	v_add_u32_e32 v196, 0x2000, v192
	v_cvt_pk_bf16_f32 v186, v186, v187
	v_cvt_pk_bf16_f32 v187, v188, v189
	ds_read_b64 v[188:189], v196 offset:1024
	ds_read_b64 v[190:191], v196 offset:1056
	v_add_u32_e32 v197, 0x2800, v192
	s_waitcnt lgkmcnt(0)
	v_mfma_f32_16x16x32_bf16 v[118:121], v[188:191], v[106:109], v[118:121]
	v_add_u32_e32 v198, 0x3000, v192
	v_cvt_pk_bf16_f32 v124, v193, v194
	v_mfma_f32_16x16x32_bf16 v[126:129], v[188:191], v[184:187], v[126:129]
	ds_read_b64 v[188:189], v197 offset:1280
	ds_read_b64 v[190:191], v197 offset:1312
	s_waitcnt lgkmcnt(0)
	v_mfma_f32_16x16x32_bf16 v[114:117], v[188:191], v[106:109], v[114:117]
	v_mfma_f32_16x16x32_bf16 v[172:175], v[188:191], v[184:187], v[172:175]
	ds_read_b64 v[188:189], v198 offset:1536
	ds_read_b64 v[190:191], v198 offset:1568
	s_waitcnt lgkmcnt(0)
	v_mfma_f32_16x16x32_bf16 v[192:195], v[188:191], v[106:109], v[110:113]
	s_nop 2
	v_add3_u32 v110, s74, v0, v171
	v_add_u32_e32 v171, 0x2000, v110
	ds_read_b64 v[110:111], v171 offset:1024
	ds_read_b64 v[112:113], v171 offset:1056
	v_mfma_f32_16x16x32_bf16 v[176:179], v[188:191], v[184:187], v[176:179]
	s_waitcnt lgkmcnt(0)
	v_mfma_f32_16x16x32_bf16 v[188:191], v[110:113], v[106:109], v[102:105]
	ds_read_b64 v[106:107], v196 offset:1088
	ds_read_b64 v[108:109], v196 offset:1120
	s_waitcnt lgkmcnt(0)
	v_mfma_f32_16x16x32_bf16 v[102:105], v[106:109], v[98:101], v[118:121]
	s_nop 2
	ds_read_b64 v[118:119], v197 offset:1344
	ds_read_b64 v[120:121], v197 offset:1376
	v_mfma_f32_16x16x32_bf16 v[180:183], v[110:113], v[184:187], v[180:183]
	v_mfma_f32_16x16x32_bf16 v[106:109], v[106:109], v[122:125], v[126:129]
	s_waitcnt lgkmcnt(0)
	v_mfma_f32_16x16x32_bf16 v[110:113], v[118:121], v[98:101], v[114:117]
	s_nop 0
	ds_read_b64 v[126:127], v198 offset:1600
	ds_read_b64 v[128:129], v198 offset:1632
	v_mfma_f32_16x16x32_bf16 v[114:117], v[118:121], v[122:125], v[172:175]
	s_nop 2
	ds_read_b64 v[172:173], v171 offset:1088
	ds_read_b64 v[174:175], v171 offset:1120
	s_waitcnt lgkmcnt(1)
	v_mfma_f32_16x16x32_bf16 v[118:121], v[126:129], v[98:101], v[192:195]
	v_mfma_f32_16x16x32_bf16 v[126:129], v[126:129], v[122:125], v[176:179]
	s_waitcnt lgkmcnt(0)
	v_mfma_f32_16x16x32_bf16 v[98:101], v[172:175], v[98:101], v[188:191]
	v_mfma_f32_16x16x32_bf16 v[122:125], v[172:175], v[122:125], v[180:183]
; template <int MODE, bool MASKED, class MaskF>
; DI void flash_tile(const u16* sK, const u16* sV, const bf16x8 (&qf)[2][2], f32x4 (&O)[2][4], float (&m)[2], float (&l)[2],
;                    float (&ps)[4][4], MaskF ok, bool sel, int lane) {
;     ...
;     float mx = -1e30f;
; #pragma unroll
;     for (int kt = 0; kt < 4; ++kt)
; #pragma unroll
;       for (int i = 0; i < 4; ++i) {
;         if (MASKED) s[kt][i] = ok(kt, i) ? s[kt][i] : -1e30f;
;         mx = fmaxf(mx, s[kt][i]);
;       }
;     if (!MASKED) mx = sel ? mx : -1e30f;
;     if (MODE == 1) {
;       const float mm = m[qt], il = l[qt];
; #pragma unroll
;       for (int kt = 0; kt < 4; ++kt)
; #pragma unroll
;         for (int i = 0; i < 4; ++i) {
;           const float pv = (s[kt][i] > -1e29f) ? __builtin_amdgcn_exp2f(s[kt][i] - mm) * il : 0.f;
;           pr[kt][i] = pv;
;           ps[kt][i] += pv;
;         }
;     } else {
;       mx = fmaxf(mx, __shfl_xor(mx, 16));
;       mx = fmaxf(mx, __shfl_xor(mx, 32));
;       const float mnew = fmaxf(m[qt], mx);
;       const float alpha = __builtin_amdgcn_exp2f(m[qt] - mnew);
;       m[qt] = mnew;
;       float rs = 0.f;
;       if (MASKED) {
; #pragma unroll
;         for (int kt = 0; kt < 4; ++kt)
; #pragma unroll
;           for (int i = 0; i < 4; ++i) {
;             const float pv = (s[kt][i] > -1e29f) ? __builtin_amdgcn_exp2f(s[kt][i] - mnew) : 0.f;
;             pr[kt][i] = pv;
;             rs += pv;
;           }
;       } else {
;         const float me = sel ? mnew : 1e30f;
; #pragma unroll
;         for (int kt = 0; kt < 4; ++kt)
; #pragma unroll
;           for (int i = 0; i < 4; ++i) {
;             const float pv = __builtin_amdgcn_exp2f(s[kt][i] - me);
;             pr[kt][i] = pv;
;             rs += pv;
;           }
;       }
;       l[qt] = l[qt] * alpha + rs;
.LBB0_844:
	s_andn2_b64 vcc, exec, s[38:39]
	s_cbranch_vccnz .LBB0_846
	s_waitcnt lgkmcnt(7)
	v_mfma_f32_16x16x32_bf16 v[98:101], v[94:97], v[4:7], 0
	s_or_b64 vcc, s[36:37], s[2:3]
	s_or_b64 s[38:39], s[36:37], s[6:7]
	s_or_b64 s[40:41], s[36:37], s[8:9]
	s_waitcnt lgkmcnt(6)
	v_mfma_f32_16x16x32_bf16 v[98:101], v[90:93], v[8:11], v[98:101]
	s_or_b64 s[42:43], s[36:37], s[10:11]
	s_or_b64 s[44:45], s[36:37], s[12:13]
	s_or_b64 s[46:47], s[36:37], s[14:15]
	s_waitcnt lgkmcnt(5)
	v_mfma_f32_16x16x32_bf16 v[102:105], v[86:89], v[4:7], 0
	s_or_b64 s[48:49], s[36:37], s[16:17]
	s_nop 1
	v_cndmask_b32_e32 v106, v98, v148, vcc
	v_cndmask_b32_e64 v2, v148, v99, s[4:5]
	v_cndmask_b32_e64 v108, v100, v148, s[38:39]
	v_cndmask_b32_e64 v109, v101, v148, s[40:41]
	s_waitcnt lgkmcnt(4)
	v_mfma_f32_16x16x32_bf16 v[98:101], v[82:85], v[8:11], v[102:105]
	v_cndmask_b32_e64 v107, v2, v148, s[36:37]
	v_max3_f32 v2, v106, s1, v107
	v_max3_f32 v2, v2, v108, v109
	s_waitcnt lgkmcnt(3)
	v_mfma_f32_16x16x32_bf16 v[102:105], v[78:81], v[4:7], 0
	s_or_b64 s[50:51], s[36:37], s[18:19]
	s_nop 1
	v_cndmask_b32_e64 v110, v98, v148, s[42:43]
	v_cndmask_b32_e64 v111, v99, v148, s[44:45]
	v_cndmask_b32_e64 v112, v100, v148, s[46:47]
	v_cndmask_b32_e64 v113, v101, v148, s[48:49]
	s_waitcnt lgkmcnt(1)
	v_mfma_f32_16x16x32_bf16 v[98:101], v[70:73], v[4:7], 0
	v_max3_f32 v2, v2, v110, v111
	s_or_b64 s[52:53], s[36:37], s[20:21]
	v_max3_f32 v2, v2, v112, v113
	v_mfma_f32_16x16x32_bf16 v[102:105], v[74:77], v[8:11], v[102:105]
	s_or_b64 s[54:55], s[36:37], s[22:23]
	s_or_b64 s[56:57], s[36:37], s[24:25]
	s_or_b64 s[58:59], s[36:37], s[26:27]
	s_waitcnt lgkmcnt(0)
	v_mfma_f32_16x16x32_bf16 v[98:101], v[66:69], v[8:11], v[98:101]
	s_or_b64 s[60:61], s[36:37], s[28:29]
	s_nop 1
	v_cndmask_b32_e64 v102, v102, v148, s[50:51]
	v_cndmask_b32_e64 v103, v103, v148, s[52:53]
	v_max3_f32 v2, v2, v102, v103
	v_cndmask_b32_e64 v104, v104, v148, s[54:55]
	v_cndmask_b32_e64 v105, v105, v148, s[56:57]
	v_max3_f32 v2, v2, v104, v105
	v_cndmask_b32_e64 v98, v98, v148, s[58:59]
	v_cndmask_b32_e64 v99, v99, v148, s[60:61]
	s_or_b64 s[62:63], s[36:37], s[30:31]
	s_or_b64 s[64:65], s[36:37], s[34:35]
	v_max3_f32 v2, v2, v98, v99
	v_cndmask_b32_e64 v100, v100, v148, s[62:63]
	v_cndmask_b32_e64 v101, v101, v148, s[64:65]
	v_max3_f32 v2, v2, v100, v101
	ds_bpermute_b32 v114, v144, v2
	v_cmp_lt_f32_e64 s[66:67], s82, v106
	v_mfma_f32_16x16x32_bf16 v[94:97], v[94:97], v[12:15], 0
	s_waitcnt lgkmcnt(0)
	v_max_f32_e32 v114, v114, v114
	v_max_f32_e32 v2, v2, v114
	ds_bpermute_b32 v114, v145, v2
	v_mfma_f32_16x16x32_bf16 v[90:93], v[90:93], v[16:19], v[94:97]
	s_waitcnt lgkmcnt(0)
	v_max3_f32 v2, v167, v2, v114
	v_sub_f32_e32 v115, v106, v2
	v_exp_f32_e32 v115, v115
	v_sub_f32_e32 v116, v107, v2
	v_exp_f32_e32 v116, v116
	v_sub_f32_e32 v117, v109, v2
	v_cndmask_b32_e64 v106, 0, v115, s[66:67]
	v_cmp_lt_f32_e64 s[66:67], s82, v107
	v_exp_f32_e32 v117, v117
	v_sub_f32_e32 v114, v167, v2
	v_cndmask_b32_e64 v107, 0, v116, s[66:67]
	v_sub_f32_e32 v116, v108, v2
	v_exp_f32_e32 v116, v116
	v_cmp_lt_f32_e64 s[66:67], s82, v108
	v_sub_f32_e32 v94, v101, v2
	v_exp_f32_e32 v97, v94
	v_cndmask_b32_e64 v108, 0, v116, s[66:67]
	v_sub_f32_e32 v116, v110, v2
	v_exp_f32_e32 v116, v116
	v_cmp_lt_f32_e64 s[66:67], s82, v109
	v_exp_f32_e32 v94, v114
	v_mfma_f32_16x16x32_bf16 v[78:81], v[78:81], v[12:15], 0
	v_cndmask_b32_e64 v109, 0, v117, s[66:67]
	v_sub_f32_e32 v117, v111, v2
	v_cmp_lt_f32_e64 s[66:67], s82, v110
	v_exp_f32_e32 v117, v117
	v_mfma_f32_16x16x32_bf16 v[70:73], v[70:73], v[12:15], 0
	v_cndmask_b32_e64 v110, 0, v116, s[66:67]
	v_sub_f32_e32 v116, v112, v2
	v_exp_f32_e32 v116, v116
	v_cmp_lt_f32_e64 s[66:67], s82, v111
	v_mfma_f32_16x16x32_bf16 v[86:89], v[86:89], v[12:15], 0
	v_add_f32_e32 v115, 0, v106
	v_cndmask_b32_e64 v111, 0, v117, s[66:67]
	v_sub_f32_e32 v117, v113, v2
	v_cmp_lt_f32_e64 s[66:67], s82, v112
	v_exp_f32_e32 v117, v117
	v_mfma_f32_16x16x32_bf16 v[74:77], v[74:77], v[16:19], v[78:81]
	v_cndmask_b32_e64 v112, 0, v116, s[66:67]
	v_sub_f32_e32 v116, v102, v2
	v_exp_f32_e32 v116, v116
	v_cmp_lt_f32_e64 s[66:67], s82, v113
	v_mfma_f32_16x16x32_bf16 v[82:85], v[82:85], v[16:19], v[86:89]
	v_add_f32_e32 v115, v107, v115
	v_cndmask_b32_e64 v113, 0, v117, s[66:67]
	v_sub_f32_e32 v117, v103, v2
	v_cmp_lt_f32_e64 s[66:67], s82, v102
	v_exp_f32_e32 v117, v117
	v_add_f32_e32 v115, v108, v115
	v_cndmask_b32_e64 v102, 0, v116, s[66:67]
	v_sub_f32_e32 v116, v104, v2
	v_exp_f32_e32 v116, v116
	v_cmp_lt_f32_e64 s[66:67], s82, v103
	v_cndmask_b32_e64 v82, v82, v148, s[42:43]
	v_cndmask_b32_e64 v83, v83, v148, s[44:45]
	v_cndmask_b32_e64 v103, 0, v117, s[66:67]
	v_sub_f32_e32 v117, v105, v2
	v_cmp_lt_f32_e64 s[66:67], s82, v104
	v_exp_f32_e32 v117, v117
	v_add_f32_e32 v115, v109, v115
	v_cndmask_b32_e64 v104, 0, v116, s[66:67]
	v_sub_f32_e32 v116, v98, v2
	v_exp_f32_e32 v116, v116
	v_cmp_lt_f32_e64 s[66:67], s82, v105
	v_cndmask_b32_e64 v84, v84, v148, s[46:47]
	v_cndmask_b32_e64 v85, v85, v148, s[48:49]
	v_cndmask_b32_e64 v105, 0, v117, s[66:67]
	v_sub_f32_e32 v117, v99, v2
	v_cmp_lt_f32_e64 s[66:67], s82, v98
	v_exp_f32_e32 v117, v117
	v_add_f32_e32 v115, v110, v115
	v_cndmask_b32_e64 v98, 0, v116, s[66:67]
	v_sub_f32_e32 v116, v100, v2
	v_exp_f32_e32 v116, v116
	v_cmp_lt_f32_e64 s[66:67], s82, v99
	v_cndmask_b32_e64 v74, v74, v148, s[50:51]
	v_cndmask_b32_e64 v75, v75, v148, s[52:53]
	v_cndmask_b32_e64 v99, 0, v117, s[66:67]
	v_cmp_lt_f32_e64 s[66:67], s82, v100
	v_add_f32_e32 v115, v111, v115
	v_cndmask_b32_e64 v76, v76, v148, s[54:55]
	v_cndmask_b32_e64 v95, 0, v116, s[66:67]
	v_mul_f32_e32 v80, v56, v94
; DI f32x4 mfma16(bf16x8 a, bf16x8 b, f32x4 c) { return __builtin_amdgcn_mfma_f32_16x16x32_bf16(a, b, c, 0, 0, 0); }
; template <int MODE, bool MASKED, class MaskF>
; DI void flash_tile(const u16* sK, const u16* sV, const bf16x8 (&qf)[2][2], f32x4 (&O)[2][4], float (&m)[2], float (&l)[2],
;                    float (&ps)[4][4], MaskF ok, bool sel, int lane) {
;     ...
;       mx = fmaxf(mx, __shfl_xor(mx, 16));
;       mx = fmaxf(mx, __shfl_xor(mx, 32));
;       const float mnew = fmaxf(m[qt], mx);
;       const float alpha = __builtin_amdgcn_exp2f(m[qt] - mnew);
;       m[qt] = mnew;
;       float rs = 0.f;
;       if (MASKED) {
; #pragma unroll
;         for (int kt = 0; kt < 4; ++kt)
; #pragma unroll
;           for (int i = 0; i < 4; ++i) {
;             const float pv = (s[kt][i] > -1e29f) ? __builtin_amdgcn_exp2f(s[kt][i] - mnew) : 0.f;
;             pr[kt][i] = pv;
;             rs += pv;
;           }
;       } else {
;         const float me = sel ? mnew : 1e30f;
; #pragma unroll
;         for (int kt = 0; kt < 4; ++kt)
; #pragma unroll
;           for (int i = 0; i < 4; ++i) {
;             const float pv = __builtin_amdgcn_exp2f(s[kt][i] - me);
;             pr[kt][i] = pv;
;             rs += pv;
;           }
;       }
;       l[qt] = l[qt] * alpha + rs;
;       if (MODE == 2) {
; #pragma unroll
;         for (int dt = 0; dt < 4; ++dt) O[qt][dt] *= alpha;
;       }
;     }
;     }
;     if (MODE != 0) {
; #pragma unroll
;       for (int ks2 = 0; ks2 < 2; ++ks2) {
;         pf[qt][ks2].u[0] = pk2(pr[2 * ks2][0], pr[2 * ks2][1]);
;         pf[qt][ks2].u[1] = pk2(pr[2 * ks2][2], pr[2 * ks2][3]);
;         pf[qt][ks2].u[2] = pk2(pr[2 * ks2 + 1][0], pr[2 * ks2 + 1][1]);
;         pf[qt][ks2].u[3] = pk2(pr[2 * ks2 + 1][2], pr[2 * ks2 + 1][3]);
;       }
;     }
;   }
;   if (MODE != 0) {
; #pragma unroll
;     for (int ks2 = 0; ks2 < 2; ++ks2) {
; #pragma unroll
;       for (int dt = 0; dt < 4; ++dt) {
;         union { uint2 h[2]; bf16x8 v; } vf;
;         vf.h[0] = *(const uint2*)(sV + (16 * dt + l15) * 72 + 32 * ks2 + 4 * lg);
;         vf.h[1] = *(const uint2*)(sV + (16 * dt + l15) * 72 + 32 * ks2 + 16 + 4 * lg);
;         O[0][dt] = mfma16(vf.v, pf[0][ks2].v, O[0][dt]);
;         O[1][dt] = mfma16(vf.v, pf[1][ks2].v, O[1][dt]);
;       }
;     }
	v_mul_f32_e32 v81, v57, v94
	v_mul_f32_e32 v78, v54, v94
	v_mul_f32_e32 v79, v55, v94
	v_mul_f32_e32 v56, v52, v94
	v_mul_f32_e32 v57, v53, v94
	v_mul_f32_e32 v54, v50, v94
	v_mul_f32_e32 v55, v51, v94
	v_mul_f32_e32 v52, v48, v94
	v_mul_f32_e32 v53, v49, v94
	v_mul_f32_e32 v50, v46, v94
	v_mul_f32_e32 v51, v47, v94
	v_mfma_f32_16x16x32_bf16 v[46:49], v[66:69], v[16:19], v[70:73]
	v_cndmask_b32_e64 v66, v148, v91, s[4:5]
	v_cndmask_b32_e64 v77, v77, v148, s[56:57]
	v_add_f32_e32 v115, v112, v115
	v_cndmask_b32_e32 v70, v90, v148, vcc
	v_cndmask_b32_e64 v71, v66, v148, s[36:37]
	v_cndmask_b32_e64 v72, v92, v148, s[38:39]
	v_cndmask_b32_e64 v73, v93, v148, s[40:41]
	s_nop 0
	v_cndmask_b32_e64 v87, v46, v148, s[58:59]
	v_max3_f32 v46, v70, s1, v71
	v_max3_f32 v46, v46, v72, v73
	v_max3_f32 v46, v46, v82, v83
	v_max3_f32 v46, v46, v84, v85
	v_max3_f32 v46, v46, v74, v75
	v_cndmask_b32_e64 v88, v47, v148, s[60:61]
	v_max3_f32 v46, v46, v76, v77
	v_add_f32_e32 v115, v113, v115
	v_cndmask_b32_e64 v89, v48, v148, s[62:63]
	v_cndmask_b32_e64 v90, v49, v148, s[64:65]
	v_max3_f32 v46, v46, v87, v88
	v_add_f32_e32 v115, v102, v115
	v_max3_f32 v66, v46, v89, v90
	v_add_f32_e32 v115, v103, v115
	ds_bpermute_b32 v67, v144, v66
	v_add_f32_e32 v115, v104, v115
	v_add_f32_e32 v115, v105, v115
	v_add_f32_e32 v115, v98, v115
	v_add_f32_e32 v115, v99, v115
	v_cmp_lt_f32_e64 s[66:67], s82, v101
	v_add_f32_e32 v96, v95, v115
	s_waitcnt lgkmcnt(0)
	v_max_f32_e32 v67, v67, v67
	v_cndmask_b32_e64 v86, 0, v97, s[66:67]
	v_add_f32_e32 v168, v86, v96
	v_cvt_pk_bf16_f32 v49, v95, v86
	v_max_f32_e32 v86, v66, v67
	ds_bpermute_b32 v91, v145, v86
	v_cmp_lt_f32_e32 vcc, s82, v70
	v_fmac_f32_e32 v168, v163, v94
	v_mul_f32_e32 v60, v60, v94
	v_mul_f32_e32 v61, v61, v94
	v_mul_f32_e32 v58, v58, v94
	v_mul_f32_e32 v59, v59, v94
	s_waitcnt lgkmcnt(0)
	v_max3_f32 v169, v166, v86, v91
	v_sub_f32_e32 v91, v70, v169
	v_exp_f32_e32 v91, v91
	v_sub_f32_e32 v92, v71, v169
	v_exp_f32_e32 v92, v92
	v_sub_f32_e32 v70, v72, v169
	v_exp_f32_e32 v70, v70
	v_cndmask_b32_e32 v91, 0, v91, vcc
	v_cmp_lt_f32_e32 vcc, s82, v71
	v_sub_f32_e32 v71, v73, v169
	v_exp_f32_e32 v71, v71
	v_cndmask_b32_e32 v92, 0, v92, vcc
	v_cmp_lt_f32_e32 vcc, s82, v72
	v_cvt_pk_bf16_f32 v48, v98, v99
	v_cvt_pk_bf16_f32 v46, v102, v103
	v_cndmask_b32_e32 v94, 0, v70, vcc
	v_sub_f32_e32 v70, v82, v169
	v_exp_f32_e32 v70, v70
	v_cmp_lt_f32_e32 vcc, s82, v73
	v_lshlrev_b32_e32 v102, 1, v153
	v_add3_u32 v3, s74, v3, v102
	v_cndmask_b32_e32 v95, 0, v71, vcc
	v_sub_f32_e32 v71, v83, v169
	v_cmp_lt_f32_e32 vcc, s82, v82
	v_exp_f32_e32 v71, v71
	v_cvt_pk_bf16_f32 v47, v104, v105
	v_cndmask_b32_e32 v96, 0, v70, vcc
	v_sub_f32_e32 v70, v84, v169
	v_exp_f32_e32 v70, v70
	v_cmp_lt_f32_e32 vcc, s82, v83
	v_add_f32_e32 v93, 0, v91
	v_add_u32_e32 v103, 0x2000, v3
	v_cndmask_b32_e32 v97, 0, v71, vcc
	v_sub_f32_e32 v71, v85, v169
	v_cmp_lt_f32_e32 vcc, s82, v84
	v_exp_f32_e32 v71, v71
	v_sub_f32_e32 v86, v166, v169
	v_cndmask_b32_e32 v98, 0, v70, vcc
	v_sub_f32_e32 v70, v74, v169
	v_exp_f32_e32 v70, v70
	v_cmp_lt_f32_e32 vcc, s82, v85
	v_exp_f32_e32 v86, v86
	v_add3_u32 v0, s74, v0, v102
	v_cndmask_b32_e32 v99, 0, v71, vcc
	v_sub_f32_e32 v71, v75, v169
	v_cmp_lt_f32_e32 vcc, s82, v74
	v_exp_f32_e32 v71, v71
	v_cvt_pk_bf16_f32 v69, v112, v113
	v_cndmask_b32_e32 v100, 0, v70, vcc
	v_sub_f32_e32 v70, v76, v169
	v_exp_f32_e32 v70, v70
	v_cmp_lt_f32_e32 vcc, s82, v75
	v_cvt_pk_bf16_f32 v66, v106, v107
	v_cvt_pk_bf16_f32 v67, v108, v109
	v_cndmask_b32_e32 v101, 0, v71, vcc
	v_sub_f32_e32 v71, v77, v169
	v_cmp_lt_f32_e32 vcc, s82, v76
	v_exp_f32_e32 v71, v71
	v_cvt_pk_bf16_f32 v68, v110, v111
	v_cndmask_b32_e32 v122, 0, v70, vcc
	v_sub_f32_e32 v70, v87, v169
	v_exp_f32_e32 v74, v70
	v_cmp_lt_f32_e32 vcc, s82, v77
	v_cvt_pk_bf16_f32 v75, v94, v95
	v_cvt_pk_bf16_f32 v76, v96, v97
	v_cndmask_b32_e32 v123, 0, v71, vcc
	v_cmp_lt_f32_e32 vcc, s82, v87
	ds_read_b64 v[70:71], v103 offset:1024
	ds_read_b64 v[72:73], v103 offset:1056
	v_cvt_pk_bf16_f32 v77, v98, v99
	v_cndmask_b32_e32 v87, 0, v74, vcc
	v_sub_f32_e32 v74, v88, v169
	v_exp_f32_e32 v104, v74
	v_cvt_pk_bf16_f32 v74, v91, v92
	v_add_u32_e32 v91, 0x2800, v3
	ds_read_b64 v[82:83], v91 offset:1280
	ds_read_b64 v[84:85], v91 offset:1312
	v_mul_f32_e32 v44, v44, v86
	v_mul_f32_e32 v45, v45, v86
	v_mul_f32_e32 v42, v42, v86
	v_mul_f32_e32 v43, v43, v86
	v_add_u32_e32 v3, 0x3000, v3
	v_mul_f32_e32 v40, v40, v86
	v_mul_f32_e32 v41, v41, v86
	v_mul_f32_e32 v38, v38, v86
	v_mul_f32_e32 v39, v39, v86
	v_add_u32_e32 v0, 0x2000, v0
	s_waitcnt lgkmcnt(1)
; DI f32x4 mfma16(bf16x8 a, bf16x8 b, f32x4 c) { return __builtin_amdgcn_mfma_f32_16x16x32_bf16(a, b, c, 0, 0, 0); }
; template <int MODE, bool MASKED, class MaskF>
; DI void flash_tile(const u16* sK, const u16* sV, const bf16x8 (&qf)[2][2], f32x4 (&O)[2][4], float (&m)[2], float (&l)[2],
;                    float (&ps)[4][4], MaskF ok, bool sel, int lane) {
;     ...
;       if (MASKED) {
; #pragma unroll
;         for (int kt = 0; kt < 4; ++kt)
; #pragma unroll
;           for (int i = 0; i < 4; ++i) {
;             const float pv = (s[kt][i] > -1e29f) ? __builtin_amdgcn_exp2f(s[kt][i] - mnew) : 0.f;
;             pr[kt][i] = pv;
;             rs += pv;
;           }
;       } else {
;         const float me = sel ? mnew : 1e30f;
; #pragma unroll
;         for (int kt = 0; kt < 4; ++kt)
; #pragma unroll
;           for (int i = 0; i < 4; ++i) {
;             const float pv = __builtin_amdgcn_exp2f(s[kt][i] - me);
;             pr[kt][i] = pv;
;             rs += pv;
;           }
;       }
;       l[qt] = l[qt] * alpha + rs;
;       if (MODE == 2) {
; #pragma unroll
;         for (int dt = 0; dt < 4; ++dt) O[qt][dt] *= alpha;
;       }
;     }
;     }
;     if (MODE != 0) {
; #pragma unroll
;       for (int ks2 = 0; ks2 < 2; ++ks2) {
;         pf[qt][ks2].u[0] = pk2(pr[2 * ks2][0], pr[2 * ks2][1]);
;         pf[qt][ks2].u[1] = pk2(pr[2 * ks2][2], pr[2 * ks2][3]);
;         pf[qt][ks2].u[2] = pk2(pr[2 * ks2 + 1][0], pr[2 * ks2 + 1][1]);
;         pf[qt][ks2].u[3] = pk2(pr[2 * ks2 + 1][2], pr[2 * ks2 + 1][3]);
;       }
;     }
;   }
;   if (MODE != 0) {
; #pragma unroll
;     for (int ks2 = 0; ks2 < 2; ++ks2) {
; #pragma unroll
;       for (int dt = 0; dt < 4; ++dt) {
;         union { uint2 h[2]; bf16x8 v; } vf;
;         vf.h[0] = *(const uint2*)(sV + (16 * dt + l15) * 72 + 32 * ks2 + 4 * lg);
;         vf.h[1] = *(const uint2*)(sV + (16 * dt + l15) * 72 + 32 * ks2 + 16 + 4 * lg);
;         O[0][dt] = mfma16(vf.v, pf[0][ks2].v, O[0][dt]);
;         O[1][dt] = mfma16(vf.v, pf[1][ks2].v, O[1][dt]);
;       }
;     }
	v_mfma_f32_16x16x32_bf16 v[58:61], v[70:73], v[66:69], v[58:61]
	v_cmp_lt_f32_e32 vcc, s82, v88
	v_mul_f32_e32 v36, v36, v86
	v_mul_f32_e32 v37, v37, v86
	v_mul_f32_e32 v34, v34, v86
	v_mul_f32_e32 v35, v35, v86
	v_mfma_f32_16x16x32_bf16 v[42:45], v[70:73], v[74:77], v[42:45]
	ds_read_b64 v[70:71], v3 offset:1536
	ds_read_b64 v[72:73], v3 offset:1568
	v_cndmask_b32_e32 v88, 0, v104, vcc
	v_sub_f32_e32 v104, v89, v169
	s_waitcnt lgkmcnt(1)
	v_mfma_f32_16x16x32_bf16 v[78:81], v[82:85], v[66:69], v[78:81]
	v_exp_f32_e32 v102, v104
	v_mul_f32_e32 v32, v32, v86
	v_mul_f32_e32 v33, v33, v86
	v_mul_f32_e32 v30, v30, v86
	v_mul_f32_e32 v31, v31, v86
	v_mfma_f32_16x16x32_bf16 v[38:41], v[82:85], v[74:77], v[38:41]
	ds_read_b64 v[82:83], v0 offset:1024
	ds_read_b64 v[84:85], v0 offset:1056
	v_cmp_lt_f32_e32 vcc, s82, v89
	s_waitcnt lgkmcnt(1)
	v_mfma_f32_16x16x32_bf16 v[54:57], v[70:73], v[66:69], v[54:57]
	v_cndmask_b32_e32 v89, 0, v102, vcc
	v_cmp_lt_f32_e32 vcc, s82, v90
	s_waitcnt lgkmcnt(0)
	v_mfma_f32_16x16x32_bf16 v[50:53], v[82:85], v[66:69], v[50:53]
	ds_read_b64 v[66:67], v103 offset:1088
	ds_read_b64 v[68:69], v103 offset:1120
	v_mfma_f32_16x16x32_bf16 v[34:37], v[70:73], v[74:77], v[34:37]
	v_sub_f32_e32 v70, v90, v169
	v_exp_f32_e32 v70, v70
	v_cvt_pk_bf16_f32 v71, v122, v123
	v_mfma_f32_16x16x32_bf16 v[30:33], v[82:85], v[74:77], v[30:33]
	ds_read_b64 v[74:75], v91 offset:1344
	ds_read_b64 v[76:77], v91 offset:1376
	v_cndmask_b32_e32 v82, 0, v70, vcc
	v_cvt_pk_bf16_f32 v70, v100, v101
	v_cvt_pk_bf16_f32 v72, v87, v88
	v_cvt_pk_bf16_f32 v73, v89, v82
	s_waitcnt lgkmcnt(1)
	v_mfma_f32_16x16x32_bf16 v[102:105], v[66:69], v[46:49], v[58:61]
	v_mfma_f32_16x16x32_bf16 v[106:109], v[66:69], v[70:73], v[42:45]
	s_nop 2
	v_add_f32_e32 v42, v92, v93
	v_add_f32_e32 v58, v94, v42
	ds_read_b64 v[42:43], v3 offset:1600
	ds_read_b64 v[44:45], v3 offset:1632
	v_add_f32_e32 v3, v95, v58
	v_add_f32_e32 v3, v96, v3
	s_waitcnt lgkmcnt(1)
	v_mfma_f32_16x16x32_bf16 v[114:117], v[74:77], v[70:73], v[38:41]
	v_add_f32_e32 v3, v97, v3
	v_add_f32_e32 v3, v98, v3
	v_add_f32_e32 v3, v99, v3
	ds_read_b64 v[38:39], v0 offset:1088
	ds_read_b64 v[40:41], v0 offset:1120
	v_add_f32_e32 v0, v100, v3
	v_add_f32_e32 v0, v101, v0
	v_add_f32_e32 v0, v122, v0
	v_add_f32_e32 v0, v123, v0
	v_add_f32_e32 v0, v87, v0
	v_mfma_f32_16x16x32_bf16 v[110:113], v[74:77], v[46:49], v[78:81]
	v_add_f32_e32 v0, v88, v0
	v_add_f32_e32 v0, v89, v0
	v_add_f32_e32 v170, v82, v0
	s_waitcnt lgkmcnt(1)
	v_mfma_f32_16x16x32_bf16 v[118:121], v[42:45], v[46:49], v[54:57]
	v_fmac_f32_e32 v170, v162, v86
	v_mfma_f32_16x16x32_bf16 v[126:129], v[42:45], v[70:73], v[34:37]
	s_waitcnt lgkmcnt(0)
	v_mfma_f32_16x16x32_bf16 v[98:101], v[38:41], v[46:49], v[50:53]
	v_mfma_f32_16x16x32_bf16 v[122:125], v[38:41], v[70:73], v[30:33]

; template <int MODE, bool MASKED, class MaskF>
; DI void flash_tile(const u16* sK, const u16* sV, const bf16x8 (&qf)[2][2], f32x4 (&O)[2][4], float (&m)[2], float (&l)[2],
;                    float (&ps)[4][4], MaskF ok, bool sel, int lane) {
;     ...
;     float mx = -1e30f;
; #pragma unroll
;     for (int kt = 0; kt < 4; ++kt)
; #pragma unroll
;       for (int i = 0; i < 4; ++i) {
;         if (MASKED) s[kt][i] = ok(kt, i) ? s[kt][i] : -1e30f;
;         mx = fmaxf(mx, s[kt][i]);
;       }
;     if (!MASKED) mx = sel ? mx : -1e30f;
;     if (MODE == 1) {
;       const float mm = m[qt], il = l[qt];
; #pragma unroll
;       for (int kt = 0; kt < 4; ++kt)
; #pragma unroll
;         for (int i = 0; i < 4; ++i) {
;           const float pv = (s[kt][i] > -1e29f) ? __builtin_amdgcn_exp2f(s[kt][i] - mm) * il : 0.f;
;           pr[kt][i] = pv;
;           ps[kt][i] += pv;
;         }
;     } else {
;       mx = fmaxf(mx, __shfl_xor(mx, 16));
;       mx = fmaxf(mx, __shfl_xor(mx, 32));
;       const float mnew = fmaxf(m[qt], mx);
;       const float alpha = __builtin_amdgcn_exp2f(m[qt] - mnew);
;       m[qt] = mnew;
;       float rs = 0.f;
;       if (MASKED) {
; #pragma unroll
;         for (int kt = 0; kt < 4; ++kt)
; #pragma unroll
;           for (int i = 0; i < 4; ++i) {
;             const float pv = (s[kt][i] > -1e29f) ? __builtin_amdgcn_exp2f(s[kt][i] - mnew) : 0.f;
;             pr[kt][i] = pv;
;             rs += pv;
;           }
;       } else {
;         const float me = sel ? mnew : 1e30f;
; #pragma unroll
;         for (int kt = 0; kt < 4; ++kt)
; #pragma unroll
;           for (int i = 0; i < 4; ++i) {
; DI void nsa_item(int wv0, PP p, int item, unsigned char* smem) {
;     ...
;     for (int j = j0; j <= i; ++j) {
;       const u16* cK = sK + cur * 9216;
;       const u16* cV = sV + cur * 9216;
;       if (j == i || j == i - 8) {
;         auto ok = [&](int kt, int ii) {
;           const int kp = j * 64 + 16 * kt + 4 * lg + ii;
;           return kp <= tq && kp > tq - 512;
;         };
;         if (usefix) flash_tile<3, true>(cK, cV, qf, O, m, l, ps, ok, true, lane);
;         else flash_tile<2, true>(cK, cV, qf, O, m, l, ps, ok, true, lane);
;       } else {
;         if (usefix) flash_tile<3, false>(cK, cV, qf, O, m, l, ps, nomask, true, lane);
;         else flash_tile<2, false>(cK, cV, qf, O, m, l, ps, nomask, true, lane);
.LBB0_904:
	s_mul_i32 s6, s85, 0x4800
	v_add_u32_e32 v25, s6, v155
	v_lshl_add_u32 v26, v0, 1, v25
	ds_read_b128 v[96:99], v26
	ds_read_b128 v[92:95], v26 offset:64
	ds_read_b128 v[88:91], v26 offset:2304
	ds_read_b128 v[84:87], v26 offset:2368
	ds_read_b128 v[80:83], v26 offset:4608
	ds_read_b128 v[76:79], v26 offset:4672
	s_add_i32 s4, s88, s84
	s_add_i32 s74, s6, 32
	v_lshl_add_u32 v25, v2, 1, v25
	s_cmpk_eq_i32 s4, 0x81
	ds_read_b128 v[72:75], v25
	ds_read_b128 v[68:71], v25 offset:64
	s_cselect_b64 s[2:3], -1, 0
	s_cmpk_eq_i32 s4, 0x79
	s_cselect_b64 s[4:5], -1, 0
	s_or_b64 s[2:3], s[2:3], s[4:5]
	v_mov_b32_e32 v60, v104
	v_mov_b32_e32 v61, v105
	v_mov_b32_e32 v62, v106
	v_mov_b32_e32 v63, v107
	v_mov_b32_e32 v52, v112
	v_mov_b32_e32 v53, v113
	v_mov_b32_e32 v54, v114
	v_mov_b32_e32 v55, v115
	v_mov_b32_e32 v44, v120
	v_mov_b32_e32 v45, v121
	v_mov_b32_e32 v46, v122
	v_mov_b32_e32 v47, v123
	v_mov_b32_e32 v36, v128
	v_mov_b32_e32 v37, v129
	v_mov_b32_e32 v38, v130
	v_mov_b32_e32 v39, v131
	v_mov_b32_e32 v64, v100
	v_mov_b32_e32 v65, v101
	v_mov_b32_e32 v66, v102
	v_mov_b32_e32 v67, v103
	v_mov_b32_e32 v56, v108
	v_mov_b32_e32 v57, v109
	v_mov_b32_e32 v58, v110
	v_mov_b32_e32 v59, v111
	v_mov_b32_e32 v48, v116
	v_mov_b32_e32 v49, v117
	v_mov_b32_e32 v50, v118
	v_mov_b32_e32 v51, v119
	v_mov_b32_e32 v40, v124
	v_mov_b32_e32 v41, v125
	v_mov_b32_e32 v42, v126
	v_mov_b32_e32 v43, v127
	s_andn2_b64 vcc, exec, s[2:3]
	s_mov_b64 s[2:3], -1
	s_cbranch_vccz .LBB0_909
	s_and_b64 vcc, exec, s[90:91]
	s_cbranch_vccz .LBB0_919
	s_waitcnt lgkmcnt(7)
	v_mfma_f32_16x16x32_bf16 v[100:103], v[96:99], v[4:7], 0
	s_waitcnt lgkmcnt(5)
	v_mfma_f32_16x16x32_bf16 v[104:107], v[88:91], v[4:7], 0
	v_mfma_f32_16x16x32_bf16 v[100:103], v[92:95], v[8:11], v[100:103]
	s_waitcnt lgkmcnt(3)
	v_mfma_f32_16x16x32_bf16 v[108:111], v[80:83], v[4:7], 0
	v_mfma_f32_16x16x32_bf16 v[104:107], v[84:87], v[8:11], v[104:107]
	s_nop 4
	v_max3_f32 v25, v100, s1, v101
	v_max3_f32 v25, v25, v102, v103
	s_waitcnt lgkmcnt(1)
	v_mfma_f32_16x16x32_bf16 v[112:115], v[72:75], v[4:7], 0
	v_mfma_f32_16x16x32_bf16 v[108:111], v[76:79], v[8:11], v[108:111]
	v_max3_f32 v25, v25, v104, v105
	v_max3_f32 v25, v25, v106, v107
	s_waitcnt lgkmcnt(0)
	v_mfma_f32_16x16x32_bf16 v[112:115], v[68:71], v[8:11], v[112:115]
	v_mfma_f32_16x16x32_bf16 v[132:135], v[80:83], v[12:15], 0
	s_nop 2
	v_max3_f32 v25, v25, v108, v109
	v_max3_f32 v25, v25, v110, v111
	s_nop 1
	v_max3_f32 v25, v25, v112, v113
	v_max3_f32 v25, v25, v114, v115
	ds_bpermute_b32 v26, v144, v25
	v_mfma_f32_16x16x32_bf16 v[160:163], v[72:75], v[12:15], 0
	s_waitcnt lgkmcnt(0)
	v_max_f32_e32 v26, v26, v26
	v_max_f32_e32 v25, v25, v26
	ds_bpermute_b32 v26, v145, v25
	v_mfma_f32_16x16x32_bf16 v[132:135], v[76:79], v[16:19], v[132:135]
	s_waitcnt lgkmcnt(0)
	v_max3_f32 v25, v28, v25, v26
	v_sub_f32_e32 v27, v100, v25
	v_exp_f32_e32 v27, v27
	v_sub_f32_e32 v30, v101, v25
	v_exp_f32_e32 v30, v30
	v_sub_f32_e32 v31, v102, v25
	v_exp_f32_e32 v31, v31
	v_sub_f32_e32 v100, v103, v25
	v_exp_f32_e32 v120, v100
	v_sub_f32_e32 v100, v104, v25
	v_add_f32_e32 v29, 0, v27
	v_exp_f32_e32 v121, v100
	v_sub_f32_e32 v100, v105, v25
	v_add_f32_e32 v29, v30, v29
	v_exp_f32_e32 v122, v100
	v_sub_f32_e32 v100, v106, v25
	v_add_f32_e32 v29, v31, v29
	v_exp_f32_e32 v123, v100
	v_sub_f32_e32 v100, v107, v25
	v_add_f32_e32 v29, v120, v29
	v_exp_f32_e32 v107, v100
	v_sub_f32_e32 v100, v108, v25
	v_add_f32_e32 v29, v121, v29
	v_exp_f32_e32 v124, v100
	v_sub_f32_e32 v100, v109, v25
	v_add_f32_e32 v29, v122, v29
	v_exp_f32_e32 v125, v100
	v_sub_f32_e32 v100, v110, v25
	v_add_f32_e32 v29, v123, v29
	v_exp_f32_e32 v126, v100
	v_sub_f32_e32 v100, v111, v25
	v_add_f32_e32 v29, v107, v29
	v_exp_f32_e32 v127, v100
	v_sub_f32_e32 v100, v112, v25
	v_add_f32_e32 v29, v124, v29
	v_exp_f32_e32 v128, v100
	v_sub_f32_e32 v100, v113, v25
	v_add_f32_e32 v29, v125, v29
	v_exp_f32_e32 v129, v100
	v_sub_f32_e32 v100, v114, v25
	v_add_f32_e32 v29, v126, v29
	v_exp_f32_e32 v130, v100
	v_sub_f32_e32 v100, v115, v25
	v_add_f32_e32 v29, v127, v29
	v_exp_f32_e32 v131, v100
	v_add_f32_e32 v29, v128, v29
	v_add_f32_e32 v29, v129, v29
	v_cvt_pk_bf16_f32 v105, v31, v120
	v_cvt_pk_bf16_f32 v106, v121, v122
	v_cvt_pk_bf16_f32 v107, v123, v107
	v_mfma_f32_16x16x32_bf16 v[120:123], v[96:99], v[12:15], 0
	v_add_f32_e32 v29, v130, v29
	v_add_f32_e32 v29, v131, v29
	v_cvt_pk_bf16_f32 v124, v124, v125
	v_cvt_pk_bf16_f32 v125, v126, v127
	v_cvt_pk_bf16_f32 v126, v128, v129
	v_cvt_pk_bf16_f32 v127, v130, v131
	v_mfma_f32_16x16x32_bf16 v[128:131], v[88:91], v[12:15], 0
	v_sub_f32_e32 v26, v28, v25
	v_exp_f32_e32 v26, v26
	v_cvt_pk_bf16_f32 v104, v27, v30
	v_mfma_f32_16x16x32_bf16 v[120:123], v[92:95], v[16:19], v[120:123]
	v_fmac_f32_e32 v29, v158, v26
	v_mul_f32_e32 v118, v62, v26
	v_mul_f32_e32 v119, v63, v26
	v_mfma_f32_16x16x32_bf16 v[128:131], v[84:87], v[16:19], v[128:131]
	v_mul_f32_e64 v116, v60, v26
	v_mul_f32_e64 v117, v61, v26
	v_mul_f32_e32 v114, v54, v26
	v_mul_f32_e32 v115, v55, v26
	v_mul_f32_e32 v112, v52, v26
	v_mul_f32_e32 v113, v53, v26
	v_mul_f32_e32 v110, v46, v26
	v_mul_f32_e32 v111, v47, v26
	v_mul_f32_e32 v108, v44, v26
	v_mul_f32_e32 v109, v45, v26
	v_mul_f32_e32 v102, v38, v26
	v_mul_f32_e32 v103, v39, v26
	v_mul_f32_e32 v100, v36, v26
	v_mul_f32_e32 v101, v37, v26
	v_max3_f32 v26, v120, s1, v121
	v_max3_f32 v26, v26, v122, v123
	v_mfma_f32_16x16x32_bf16 v[160:163], v[68:71], v[16:19], v[160:163]
	v_max3_f32 v26, v26, v128, v129
	v_max3_f32 v26, v26, v130, v131
	v_max3_f32 v26, v26, v132, v133
	v_max3_f32 v26, v26, v134, v135
	s_nop 3
	v_max3_f32 v26, v26, v160, v161
	v_max3_f32 v26, v26, v162, v163
	ds_bpermute_b32 v27, v144, v26
	s_waitcnt lgkmcnt(0)
; DI f32x4 mfma16(bf16x8 a, bf16x8 b, f32x4 c) { return __builtin_amdgcn_mfma_f32_16x16x32_bf16(a, b, c, 0, 0, 0); }
; template <int MODE, bool MASKED, class MaskF>
; DI void flash_tile(const u16* sK, const u16* sV, const bf16x8 (&qf)[2][2], f32x4 (&O)[2][4], float (&m)[2], float (&l)[2],
;                    float (&ps)[4][4], MaskF ok, bool sel, int lane) {
;     ...
;       mx = fmaxf(mx, __shfl_xor(mx, 16));
;       mx = fmaxf(mx, __shfl_xor(mx, 32));
;       const float mnew = fmaxf(m[qt], mx);
;       const float alpha = __builtin_amdgcn_exp2f(m[qt] - mnew);
;       m[qt] = mnew;
;       float rs = 0.f;
;       if (MASKED) {
; #pragma unroll
;         for (int kt = 0; kt < 4; ++kt)
; #pragma unroll
;           for (int i = 0; i < 4; ++i) {
;             const float pv = (s[kt][i] > -1e29f) ? __builtin_amdgcn_exp2f(s[kt][i] - mnew) : 0.f;
;             pr[kt][i] = pv;
;             rs += pv;
;           }
;       } else {
;         const float me = sel ? mnew : 1e30f;
; #pragma unroll
;         for (int kt = 0; kt < 4; ++kt)
; #pragma unroll
;           for (int i = 0; i < 4; ++i) {
;             const float pv = __builtin_amdgcn_exp2f(s[kt][i] - me);
;             pr[kt][i] = pv;
;             rs += pv;
;           }
;       }
;       l[qt] = l[qt] * alpha + rs;
;       if (MODE == 2) {
; #pragma unroll
;         for (int dt = 0; dt < 4; ++dt) O[qt][dt] *= alpha;
;       }
;     }
;     }
;     if (MODE != 0) {
; #pragma unroll
;       for (int ks2 = 0; ks2 < 2; ++ks2) {
;         pf[qt][ks2].u[0] = pk2(pr[2 * ks2][0], pr[2 * ks2][1]);
;         pf[qt][ks2].u[1] = pk2(pr[2 * ks2][2], pr[2 * ks2][3]);
;         pf[qt][ks2].u[2] = pk2(pr[2 * ks2 + 1][0], pr[2 * ks2 + 1][1]);
;         pf[qt][ks2].u[3] = pk2(pr[2 * ks2 + 1][2], pr[2 * ks2 + 1][3]);
;       }
;     }
;   }
;   if (MODE != 0) {
; #pragma unroll
;     for (int ks2 = 0; ks2 < 2; ++ks2) {
; #pragma unroll
;       for (int dt = 0; dt < 4; ++dt) {
;         union { uint2 h[2]; bf16x8 v; } vf;
;         vf.h[0] = *(const uint2*)(sV + (16 * dt + l15) * 72 + 32 * ks2 + 4 * lg);
;         vf.h[1] = *(const uint2*)(sV + (16 * dt + l15) * 72 + 32 * ks2 + 16 + 4 * lg);
;         O[0][dt] = mfma16(vf.v, pf[0][ks2].v, O[0][dt]);
;         O[1][dt] = mfma16(vf.v, pf[1][ks2].v, O[1][dt]);
;       }
;     }
	v_max_f32_e32 v27, v27, v27
	v_max_f32_e32 v26, v26, v27
	ds_bpermute_b32 v27, v145, v26
	s_waitcnt lgkmcnt(0)
	v_max3_f32 v27, v24, v26, v27
	v_sub_f32_e32 v26, v120, v27
	v_exp_f32_e32 v31, v26
	v_sub_f32_e32 v120, v121, v27
	v_exp_f32_e32 v159, v120
	v_sub_f32_e32 v120, v122, v27
	v_exp_f32_e32 v169, v120
	v_sub_f32_e32 v120, v123, v27
	v_exp_f32_e32 v170, v120
	v_sub_f32_e32 v120, v128, v27
	v_add_f32_e32 v26, 0, v31
	v_exp_f32_e32 v171, v120
	v_sub_f32_e32 v120, v129, v27
	v_add_f32_e32 v26, v159, v26
	v_exp_f32_e32 v172, v120
	v_sub_f32_e32 v120, v130, v27
	v_add_f32_e32 v26, v169, v26
	v_exp_f32_e32 v173, v120
	v_sub_f32_e32 v120, v131, v27
	v_add_f32_e32 v26, v170, v26
	v_exp_f32_e32 v174, v120
	v_sub_f32_e32 v120, v132, v27
	v_add_f32_e32 v26, v171, v26
	v_exp_f32_e32 v132, v120
	v_sub_f32_e32 v120, v133, v27
	v_add_f32_e32 v26, v172, v26
	v_exp_f32_e32 v133, v120
	v_sub_f32_e32 v120, v134, v27
	v_add_f32_e32 v26, v173, v26
	v_exp_f32_e32 v134, v120
	v_sub_f32_e32 v120, v135, v27
	v_add_f32_e32 v26, v174, v26
	v_exp_f32_e32 v135, v120
	v_sub_f32_e32 v120, v160, v27
	v_add_f32_e32 v26, v132, v26
	v_exp_f32_e32 v175, v120
	v_sub_f32_e32 v120, v161, v27
	v_add_f32_e32 v26, v133, v26
	v_exp_f32_e32 v176, v120
	v_sub_f32_e32 v120, v162, v27
	v_add_f32_e32 v26, v134, v26
	v_exp_f32_e32 v177, v120
	v_sub_f32_e32 v120, v163, v27
	v_sub_f32_e32 v30, v24, v27
	v_add_f32_e32 v26, v135, v26
	v_exp_f32_e32 v178, v120
	v_add_f32_e32 v26, v175, v26
	v_exp_f32_e32 v30, v30
	v_add_f32_e32 v26, v176, v26
	v_add_f32_e32 v26, v177, v26
	v_add_f32_e32 v26, v178, v26
	v_fmac_f32_e32 v26, v157, v30
	v_mul_f32_e32 v122, v66, v30
	v_mul_f32_e32 v123, v67, v30
	v_mul_f32_e32 v120, v64, v30
	v_mul_f32_e32 v121, v65, v30
	v_mul_f32_e32 v130, v58, v30
	v_mul_f32_e32 v131, v59, v30
	v_mul_f32_e32 v128, v56, v30
	v_mul_f32_e32 v129, v57, v30
	v_mul_f32_e32 v162, v50, v30
	v_mul_f32_e32 v163, v51, v30
	v_mul_f32_e32 v160, v48, v30
	v_mul_f32_e32 v161, v49, v30
	v_mul_f32_e32 v166, v42, v30
	v_mul_f32_e32 v167, v43, v30
	v_mul_f32_e32 v164, v40, v30
	v_mul_f32_e32 v165, v41, v30
	v_cvt_pk_bf16_f32 v168, v31, v159
	v_lshlrev_b32_e32 v30, 1, v0
	v_lshlrev_b32_e32 v31, 1, v153
	v_add3_u32 v30, s74, v30, v31
	v_add_u32_e32 v159, 0x2000, v30
	v_cvt_pk_bf16_f32 v169, v169, v170
	v_cvt_pk_bf16_f32 v170, v171, v172
	v_cvt_pk_bf16_f32 v171, v173, v174
	v_cvt_pk_bf16_f32 v132, v132, v133
	v_cvt_pk_bf16_f32 v133, v134, v135
	v_cvt_pk_bf16_f32 v134, v175, v176
	ds_read_b64 v[172:173], v159 offset:1024
	ds_read_b64 v[174:175], v159 offset:1056
	v_add_u32_e32 v180, 0x2800, v30
	s_waitcnt lgkmcnt(0)
	v_mfma_f32_16x16x32_bf16 v[116:119], v[172:175], v[104:107], v[116:119]
	v_add_u32_e32 v30, 0x3000, v30
	v_cvt_pk_bf16_f32 v135, v177, v178
	v_mfma_f32_16x16x32_bf16 v[120:123], v[172:175], v[168:171], v[120:123]
	ds_read_b64 v[172:173], v180 offset:1280
	ds_read_b64 v[174:175], v180 offset:1312
	s_waitcnt lgkmcnt(0)
	v_mfma_f32_16x16x32_bf16 v[112:115], v[172:175], v[104:107], v[112:115]
	v_mfma_f32_16x16x32_bf16 v[128:131], v[172:175], v[168:171], v[128:131]
	ds_read_b64 v[172:173], v30 offset:1536
	ds_read_b64 v[174:175], v30 offset:1568
	s_waitcnt lgkmcnt(0)
	v_mfma_f32_16x16x32_bf16 v[176:179], v[172:175], v[104:107], v[108:111]
	s_nop 2
	v_lshlrev_b32_e32 v108, 1, v2
	v_add3_u32 v31, s74, v108, v31
	v_add_u32_e32 v31, 0x2000, v31
	ds_read_b64 v[108:109], v31 offset:1024
	ds_read_b64 v[110:111], v31 offset:1056
	v_mfma_f32_16x16x32_bf16 v[160:163], v[172:175], v[168:171], v[160:163]
	s_waitcnt lgkmcnt(0)
	v_mfma_f32_16x16x32_bf16 v[172:175], v[108:111], v[104:107], v[100:103]
	s_nop 2
	ds_read_b64 v[100:101], v159 offset:1088
	ds_read_b64 v[102:103], v159 offset:1120
	s_waitcnt lgkmcnt(0)
	v_mfma_f32_16x16x32_bf16 v[104:107], v[100:103], v[124:127], v[116:119]
	s_nop 2
	ds_read_b64 v[116:117], v30 offset:1600
	ds_read_b64 v[118:119], v30 offset:1632
	v_mfma_f32_16x16x32_bf16 v[164:167], v[108:111], v[168:171], v[164:167]
	ds_read_b64 v[108:109], v180 offset:1344
	ds_read_b64 v[110:111], v180 offset:1376
	v_mfma_f32_16x16x32_bf16 v[100:103], v[100:103], v[132:135], v[120:123]
	s_waitcnt lgkmcnt(1)
	v_mfma_f32_16x16x32_bf16 v[120:123], v[116:119], v[124:127], v[176:179]
	v_mfma_f32_16x16x32_bf16 v[116:119], v[116:119], v[132:135], v[160:163]
	s_nop 2
	ds_read_b64 v[160:161], v31 offset:1088
	ds_read_b64 v[162:163], v31 offset:1120
	s_waitcnt lgkmcnt(1)
	v_mfma_f32_16x16x32_bf16 v[112:115], v[108:111], v[124:127], v[112:115]
	v_mfma_f32_16x16x32_bf16 v[108:111], v[108:111], v[132:135], v[128:131]
	s_waitcnt lgkmcnt(0)
	v_mfma_f32_16x16x32_bf16 v[128:131], v[160:163], v[124:127], v[172:175]
	v_mfma_f32_16x16x32_bf16 v[124:127], v[160:163], v[132:135], v[164:167]
	s_cbranch_execnz .LBB0_908

; DI f32x4 mfma16(bf16x8 a, bf16x8 b, f32x4 c) { return __builtin_amdgcn_mfma_f32_16x16x32_bf16(a, b, c, 0, 0, 0); }
; template <int MODE, bool MASKED, class MaskF>
; DI void flash_tile(const u16* sK, const u16* sV, const bf16x8 (&qf)[2][2], f32x4 (&O)[2][4], float (&m)[2], float (&l)[2],
;                    float (&ps)[4][4], MaskF ok, bool sel, int lane) {
;     ...
;     for (int kt = 0; kt < 4; ++kt) {
;       s[kt] = f32x4{sinit, sinit, sinit, sinit};
; #pragma unroll
;       for (int ks = 0; ks < 2; ++ks) s[kt] = mfma16(kf[kt][ks], qf[qt][ks], s[kt]);
;     }
;     float pr[4][4];
;     if (MODE == 3) {
;       float rs = 0.f;
; #pragma unroll
;       for (int kt = 0; kt < 4; ++kt)
; #pragma unroll
;         for (int i = 0; i < 4; ++i) {
;           float pv = __builtin_amdgcn_exp2f(s[kt][i]);
;           if (MASKED) pv = ok(kt, i) ? pv : 0.f;
;           pr[kt][i] = pv;
;           rs += pv;
;         }
;       l[qt] += rs;
;     } else {
;     float mx = -1e30f;
; #pragma unroll
;     for (int kt = 0; kt < 4; ++kt)
; #pragma unroll
;       for (int i = 0; i < 4; ++i) {
;         if (MASKED) s[kt][i] = ok(kt, i) ? s[kt][i] : -1e30f;
;         mx = fmaxf(mx, s[kt][i]);
;       }
;     if (!MASKED) mx = sel ? mx : -1e30f;
;     if (MODE == 1) {
;       const float mm = m[qt], il = l[qt];
; #pragma unroll
;       for (int kt = 0; kt < 4; ++kt)
; #pragma unroll
;         for (int i = 0; i < 4; ++i) {
;           const float pv = (s[kt][i] > -1e29f) ? __builtin_amdgcn_exp2f(s[kt][i] - mm) * il : 0.f;
;           pr[kt][i] = pv;
;           ps[kt][i] += pv;
;         }
;     } else {
;       mx = fmaxf(mx, __shfl_xor(mx, 16));
;       mx = fmaxf(mx, __shfl_xor(mx, 32));
; DI void nsa_item(int wv0, PP p, int item, unsigned char* smem) {
;     ...
;       if (j == i || j == i - 8) {
;         auto ok = [&](int kt, int ii) {
;           const int kp = j * 64 + 16 * kt + 4 * lg + ii;
;           return kp <= tq && kp > tq - 512;
;         };
;         if (usefix) flash_tile<3, true>(cK, cV, qf, O, m, l, ps, ok, true, lane);
;         else flash_tile<2, true>(cK, cV, qf, O, m, l, ps, ok, true, lane);
.LBB0_909:
	s_andn2_b64 vcc, exec, s[2:3]
	s_cbranch_vccnz .LBB0_913
	v_subrev_u32_e32 v171, 51, v156
	v_subrev_u32_e32 v170, 49, v156
	v_subrev_u32_e32 v169, 48, v156
	v_subrev_u32_e32 v168, 35, v156
	v_subrev_u32_e32 v167, 34, v156
	v_subrev_u32_e32 v166, 33, v156
	v_subrev_u32_e32 v165, 32, v156
	v_subrev_u32_e32 v164, 19, v156
	v_subrev_u32_e32 v163, 18, v156
	v_subrev_u32_e32 v162, 17, v156
	v_add_u32_e32 v161, -16, v156
	v_add_u32_e32 v160, -3, v156
	v_add_u32_e32 v159, -2, v156
	v_add_u32_e32 v135, -1, v156
	s_and_b64 vcc, exec, s[90:91]
	v_cmp_le_i32_e64 s[30:31], v156, v151
	v_cmp_gt_i32_e64 s[34:35], v156, v3
	v_cmp_le_i32_e64 s[64:65], v171, v151
	v_cmp_gt_i32_e64 s[66:67], v171, v3
	v_cmp_lt_i32_e64 s[2:3], v171, v151
	v_cmp_ge_i32_e64 s[62:63], v171, v3
	v_cmp_le_i32_e64 s[4:5], v170, v151
	v_cmp_gt_i32_e64 s[60:61], v170, v3
	v_cmp_le_i32_e64 s[6:7], v169, v151
	v_cmp_gt_i32_e64 s[58:59], v169, v3
	v_cmp_le_i32_e64 s[8:9], v168, v151
	v_cmp_gt_i32_e64 s[56:57], v168, v3
	v_cmp_le_i32_e64 s[10:11], v167, v151
	v_cmp_gt_i32_e64 s[54:55], v167, v3
	v_cmp_le_i32_e64 s[12:13], v166, v151
	v_cmp_gt_i32_e64 s[52:53], v166, v3
	v_cmp_le_i32_e64 s[14:15], v165, v151
	v_cmp_gt_i32_e64 s[50:51], v165, v3
	v_cmp_le_i32_e64 s[16:17], v164, v151
	v_cmp_gt_i32_e64 s[48:49], v164, v3
	v_cmp_le_i32_e64 s[18:19], v163, v151
	v_cmp_gt_i32_e64 s[46:47], v163, v3
	v_cmp_le_i32_e64 s[20:21], v162, v151
	v_cmp_gt_i32_e64 s[42:43], v162, v3
	v_cmp_le_i32_e64 s[22:23], v161, v151
	v_cmp_gt_i32_e64 s[44:45], v161, v3
	v_cmp_le_i32_e64 s[24:25], v160, v151
	v_cmp_gt_i32_e64 s[38:39], v160, v3
	v_cmp_le_i32_e64 s[26:27], v159, v151
	v_cmp_gt_i32_e64 s[40:41], v159, v3
	v_cmp_le_i32_e64 s[28:29], v135, v151
	v_cmp_gt_i32_e64 s[36:37], v135, v3
	v_lshlrev_b32_e32 v134, 1, v0
	v_lshlrev_b32_e32 v132, 1, v153
	v_lshlrev_b32_e32 v133, 1, v2
	s_cbranch_vccz .LBB0_920
	s_waitcnt lgkmcnt(7)
	v_mfma_f32_16x16x32_bf16 v[100:103], v[96:99], v[4:7], 0
	s_and_b64 vcc, s[64:65], s[66:67]
	s_and_b64 s[2:3], s[2:3], s[62:63]
	s_and_b64 s[4:5], s[4:5], s[60:61]
	s_waitcnt lgkmcnt(6)
	v_mfma_f32_16x16x32_bf16 v[100:103], v[92:95], v[8:11], v[100:103]
	s_and_b64 s[6:7], s[6:7], s[58:59]
	s_and_b64 s[8:9], s[8:9], s[56:57]
	s_and_b64 s[10:11], s[10:11], s[54:55]
	s_waitcnt lgkmcnt(5)
	v_mfma_f32_16x16x32_bf16 v[104:107], v[88:91], v[4:7], 0
	s_and_b64 s[12:13], s[12:13], s[52:53]
	s_nop 1
	v_cndmask_b32_e32 v26, v148, v100, vcc
	v_cndmask_b32_e64 v27, v148, v101, s[2:3]
	v_cndmask_b32_e64 v29, v148, v102, s[4:5]
	v_cndmask_b32_e64 v30, v148, v103, s[6:7]
	s_waitcnt lgkmcnt(4)
	v_mfma_f32_16x16x32_bf16 v[100:103], v[84:87], v[8:11], v[104:107]
	s_and_b64 s[14:15], s[14:15], s[50:51]
	v_max3_f32 v25, v26, s1, v27
	v_max3_f32 v25, v25, v29, v30
	s_waitcnt lgkmcnt(3)
	v_mfma_f32_16x16x32_bf16 v[104:107], v[80:83], v[4:7], 0
	s_and_b64 s[16:17], s[16:17], s[48:49]
	s_nop 1
	v_cndmask_b32_e64 v31, v148, v100, s[8:9]
	v_cndmask_b32_e64 v108, v148, v101, s[10:11]
	v_cndmask_b32_e64 v109, v148, v102, s[12:13]
	v_cndmask_b32_e64 v110, v148, v103, s[14:15]
	s_waitcnt lgkmcnt(1)
	v_mfma_f32_16x16x32_bf16 v[100:103], v[72:75], v[4:7], 0
	v_max3_f32 v25, v25, v31, v108
	s_and_b64 s[18:19], s[18:19], s[46:47]
	v_max3_f32 v25, v25, v109, v110
	v_mfma_f32_16x16x32_bf16 v[104:107], v[76:79], v[8:11], v[104:107]
	s_and_b64 s[20:21], s[20:21], s[42:43]
	s_and_b64 s[22:23], s[22:23], s[44:45]
	s_and_b64 s[24:25], s[24:25], s[38:39]
	s_waitcnt lgkmcnt(0)
	v_mfma_f32_16x16x32_bf16 v[100:103], v[68:71], v[8:11], v[100:103]
	s_and_b64 s[26:27], s[26:27], s[40:41]
	s_nop 1
	v_cndmask_b32_e64 v104, v148, v104, s[16:17]
	v_cndmask_b32_e64 v105, v148, v105, s[18:19]
	v_max3_f32 v25, v25, v104, v105
	v_cndmask_b32_e64 v106, v148, v106, s[20:21]
	v_cndmask_b32_e64 v107, v148, v107, s[22:23]
	v_max3_f32 v25, v25, v106, v107
	v_cndmask_b32_e64 v100, v148, v100, s[24:25]
	v_cndmask_b32_e64 v101, v148, v101, s[26:27]
	s_and_b64 s[28:29], s[28:29], s[36:37]
	s_and_b64 s[30:31], s[30:31], s[34:35]
	v_max3_f32 v25, v25, v100, v101
	v_cndmask_b32_e64 v112, v148, v102, s[28:29]
	v_cndmask_b32_e64 v116, v148, v103, s[30:31]
	v_max3_f32 v25, v25, v112, v116
	ds_bpermute_b32 v102, v144, v25
	v_cmp_lt_f32_e64 s[34:35], s82, v26
	v_mfma_f32_16x16x32_bf16 v[124:127], v[72:75], v[12:15], 0
	s_waitcnt lgkmcnt(0)
	v_max_f32_e32 v102, v102, v102
	v_max_f32_e32 v25, v25, v102
	ds_bpermute_b32 v102, v145, v25
	v_mfma_f32_16x16x32_bf16 v[124:127], v[68:71], v[16:19], v[124:127]
	s_waitcnt lgkmcnt(0)
; template <int MODE, bool MASKED, class MaskF>
; DI void flash_tile(const u16* sK, const u16* sV, const bf16x8 (&qf)[2][2], f32x4 (&O)[2][4], float (&m)[2], float (&l)[2],
;                    float (&ps)[4][4], MaskF ok, bool sel, int lane) {
;     ...
;       mx = fmaxf(mx, __shfl_xor(mx, 16));
;       mx = fmaxf(mx, __shfl_xor(mx, 32));
;       const float mnew = fmaxf(m[qt], mx);
;       const float alpha = __builtin_amdgcn_exp2f(m[qt] - mnew);
;       m[qt] = mnew;
;       float rs = 0.f;
;       if (MASKED) {
; #pragma unroll
;         for (int kt = 0; kt < 4; ++kt)
; #pragma unroll
;           for (int i = 0; i < 4; ++i) {
;             const float pv = (s[kt][i] > -1e29f) ? __builtin_amdgcn_exp2f(s[kt][i] - mnew) : 0.f;
;             pr[kt][i] = pv;
;             rs += pv;
;           }
;       } else {
;         const float me = sel ? mnew : 1e30f;
; #pragma unroll
;         for (int kt = 0; kt < 4; ++kt)
; #pragma unroll
;           for (int i = 0; i < 4; ++i) {
;             const float pv = __builtin_amdgcn_exp2f(s[kt][i] - me);
;             pr[kt][i] = pv;
;             rs += pv;
;           }
;       }
;       l[qt] = l[qt] * alpha + rs;
;       if (MODE == 2) {
; #pragma unroll
;         for (int dt = 0; dt < 4; ++dt) O[qt][dt] *= alpha;
	v_max3_f32 v25, v28, v25, v102
	v_sub_f32_e32 v102, v26, v25
	v_exp_f32_e32 v102, v102
	v_sub_f32_e32 v103, v27, v25
	v_exp_f32_e32 v103, v103
	v_sub_f32_e32 v113, v28, v25
	v_cndmask_b32_e64 v172, 0, v102, s[34:35]
	v_sub_f32_e32 v102, v29, v25
	v_exp_f32_e32 v102, v102
	v_cmp_lt_f32_e64 s[34:35], s82, v27
	v_add_f32_e32 v26, 0, v172
	v_cndmask_b32_e64 v188, v148, v124, s[24:25]
	v_cndmask_b32_e64 v27, 0, v103, s[34:35]
	v_sub_f32_e32 v103, v30, v25
	v_exp_f32_e32 v103, v103
	v_cmp_lt_f32_e64 s[34:35], s82, v29
	v_sub_f32_e32 v29, v31, v25
	v_exp_f32_e32 v29, v29
	v_cndmask_b32_e64 v173, 0, v102, s[34:35]
	v_sub_f32_e32 v102, v108, v25
	v_exp_f32_e32 v102, v102
	v_cmp_lt_f32_e64 s[34:35], s82, v30
	v_add_f32_e32 v26, v27, v26
	v_add_f32_e32 v26, v173, v26
	v_cndmask_b32_e64 v30, 0, v103, s[34:35]
	v_cmp_lt_f32_e64 s[34:35], s82, v31
	v_add_f32_e32 v26, v30, v26
	v_cndmask_b32_e64 v189, v148, v125, s[26:27]
	v_cndmask_b32_e64 v31, 0, v29, s[34:35]
	v_cmp_lt_f32_e64 s[34:35], s82, v108
	v_sub_f32_e32 v29, v109, v25
	v_exp_f32_e32 v29, v29
	v_cndmask_b32_e64 v174, 0, v102, s[34:35]
	v_sub_f32_e32 v102, v110, v25
	v_exp_f32_e32 v102, v102
	v_cmp_lt_f32_e64 s[34:35], s82, v109
	v_add_f32_e32 v26, v31, v26
	v_add_f32_e32 v26, v174, v26
	v_cndmask_b32_e64 v175, 0, v29, s[34:35]
	v_cmp_lt_f32_e64 s[34:35], s82, v110
	v_sub_f32_e32 v29, v104, v25
	v_exp_f32_e32 v29, v29
	v_cndmask_b32_e64 v176, 0, v102, s[34:35]
	v_sub_f32_e32 v102, v105, v25
	v_exp_f32_e32 v102, v102
	v_cmp_lt_f32_e64 s[34:35], s82, v104
	v_add_f32_e32 v26, v175, v26
	v_add_f32_e32 v26, v176, v26
	v_cndmask_b32_e64 v177, 0, v29, s[34:35]
	v_cmp_lt_f32_e64 s[34:35], s82, v105
	v_sub_f32_e32 v29, v106, v25
	v_exp_f32_e32 v29, v29
	v_cndmask_b32_e64 v178, 0, v102, s[34:35]
	v_sub_f32_e32 v102, v107, v25
	v_exp_f32_e32 v102, v102
	v_cmp_lt_f32_e64 s[34:35], s82, v106
	v_add_f32_e32 v26, v177, v26
	v_add_f32_e32 v26, v178, v26
	v_cndmask_b32_e64 v179, 0, v29, s[34:35]
	v_cmp_lt_f32_e64 s[34:35], s82, v107
	v_sub_f32_e32 v29, v100, v25
	v_exp_f32_e32 v29, v29
	v_cndmask_b32_e64 v180, 0, v102, s[34:35]
	v_sub_f32_e32 v102, v101, v25
	v_exp_f32_e32 v102, v102
	v_cmp_lt_f32_e64 s[34:35], s82, v100
	v_add_f32_e32 v26, v179, v26
	v_add_f32_e32 v26, v180, v26
	v_cndmask_b32_e64 v181, 0, v29, s[34:35]
	v_cmp_lt_f32_e64 s[34:35], s82, v101
	v_sub_f32_e32 v29, v112, v25
	v_exp_f32_e32 v29, v29
	v_cndmask_b32_e64 v182, 0, v102, s[34:35]
	v_mfma_f32_16x16x32_bf16 v[100:103], v[96:99], v[12:15], 0
	v_add_f32_e32 v26, v181, v26
	v_cmp_lt_f32_e64 s[34:35], s82, v112
	v_add_f32_e32 v26, v182, v26
	v_mfma_f32_16x16x32_bf16 v[108:111], v[92:95], v[16:19], v[100:103]
	v_cndmask_b32_e64 v183, 0, v29, s[34:35]
	v_add_f32_e32 v29, v183, v26
	v_sub_f32_e32 v26, v116, v25
	v_mfma_f32_16x16x32_bf16 v[100:103], v[88:91], v[12:15], 0
	v_exp_f32_e32 v104, v26
	v_exp_f32_e32 v26, v113
	v_cmp_lt_f32_e64 s[34:35], s82, v116
	v_mfma_f32_16x16x32_bf16 v[112:115], v[84:87], v[16:19], v[100:103]
	v_cndmask_b32_e64 v185, v148, v109, s[2:3]
	v_cndmask_b32_e64 v184, 0, v104, s[34:35]
	v_add_f32_e32 v29, v184, v29
	v_mfma_f32_16x16x32_bf16 v[100:103], v[80:83], v[12:15], 0
	v_fmac_f32_e32 v29, v158, v26
	v_mul_f32_e32 v118, v62, v26
	v_mul_f32_e32 v119, v63, v26
	v_mul_f32_e32 v116, v60, v26
	v_mul_f32_e32 v117, v61, v26
	v_mfma_f32_16x16x32_bf16 v[120:123], v[76:79], v[16:19], v[100:103]
	v_mul_f32_e64 v130, v54, v26
	v_mul_f32_e64 v131, v55, v26
	v_mul_f32_e32 v128, v52, v26
	v_mul_f32_e32 v129, v53, v26
	v_mul_f32_e32 v106, v46, v26
	v_mul_f32_e32 v107, v47, v26
	v_mul_f32_e32 v104, v44, v26
	v_mul_f32_e32 v105, v45, v26
	v_mul_f32_e32 v102, v38, v26
	v_mul_f32_e32 v103, v39, v26
	v_mul_f32_e32 v100, v36, v26
	v_mul_f32_e32 v101, v37, v26
	v_cndmask_b32_e32 v26, v148, v108, vcc
	v_cndmask_b32_e64 v186, v148, v110, s[4:5]
	v_cndmask_b32_e64 v187, v148, v111, s[6:7]
	v_max3_f32 v108, v26, s1, v185
	v_cndmask_b32_e64 v112, v148, v112, s[8:9]
	v_cndmask_b32_e64 v113, v148, v113, s[10:11]
	v_max3_f32 v108, v108, v186, v187
	v_cndmask_b32_e64 v114, v148, v114, s[12:13]
	v_cndmask_b32_e64 v115, v148, v115, s[14:15]
	v_max3_f32 v108, v108, v112, v113
	v_cndmask_b32_e64 v120, v148, v120, s[16:17]
	v_cndmask_b32_e64 v121, v148, v121, s[18:19]
	v_max3_f32 v108, v108, v114, v115
	v_cndmask_b32_e64 v122, v148, v122, s[20:21]
	v_cndmask_b32_e64 v123, v148, v123, s[22:23]
	v_max3_f32 v108, v108, v120, v121
	v_max3_f32 v108, v108, v122, v123
	v_cndmask_b32_e64 v192, v148, v126, s[28:29]
	v_cndmask_b32_e64 v196, v148, v127, s[30:31]
	v_max3_f32 v108, v108, v188, v189
	v_max3_f32 v108, v108, v192, v196
	ds_bpermute_b32 v109, v144, v108
	v_cvt_pk_bf16_f32 v124, v177, v178
	v_cvt_pk_bf16_f32 v110, v31, v174
	v_cmp_lt_f32_e32 vcc, s82, v26
	v_cvt_pk_bf16_f32 v125, v179, v180
	s_waitcnt lgkmcnt(0)
	v_max_f32_e32 v109, v109, v109
	v_max_f32_e32 v177, v108, v109
	ds_bpermute_b32 v178, v145, v177
	v_cvt_pk_bf16_f32 v108, v172, v27
	v_cvt_pk_bf16_f32 v109, v173, v30
	v_add3_u32 v180, s74, v134, v132
	v_add_u32_e32 v208, 0x2000, v180
	s_waitcnt lgkmcnt(0)
; DI f32x4 mfma16(bf16x8 a, bf16x8 b, f32x4 c) { return __builtin_amdgcn_mfma_f32_16x16x32_bf16(a, b, c, 0, 0, 0); }
; template <int MODE, bool MASKED, class MaskF>
; DI void flash_tile(const u16* sK, const u16* sV, const bf16x8 (&qf)[2][2], f32x4 (&O)[2][4], float (&m)[2], float (&l)[2],
;                    float (&ps)[4][4], MaskF ok, bool sel, int lane) {
;     ...
;       mx = fmaxf(mx, __shfl_xor(mx, 16));
;       mx = fmaxf(mx, __shfl_xor(mx, 32));
;       const float mnew = fmaxf(m[qt], mx);
;       const float alpha = __builtin_amdgcn_exp2f(m[qt] - mnew);
;       m[qt] = mnew;
;       float rs = 0.f;
;       if (MASKED) {
; #pragma unroll
;         for (int kt = 0; kt < 4; ++kt)
; #pragma unroll
;           for (int i = 0; i < 4; ++i) {
;             const float pv = (s[kt][i] > -1e29f) ? __builtin_amdgcn_exp2f(s[kt][i] - mnew) : 0.f;
;             pr[kt][i] = pv;
;             rs += pv;
;           }
;       } else {
;         const float me = sel ? mnew : 1e30f;
; #pragma unroll
;         for (int kt = 0; kt < 4; ++kt)
; #pragma unroll
;           for (int i = 0; i < 4; ++i) {
;             const float pv = __builtin_amdgcn_exp2f(s[kt][i] - me);
;             pr[kt][i] = pv;
;             rs += pv;
;           }
;       }
;       l[qt] = l[qt] * alpha + rs;
;       if (MODE == 2) {
; #pragma unroll
;         for (int dt = 0; dt < 4; ++dt) O[qt][dt] *= alpha;
;       }
;     }
;     }
;     if (MODE != 0) {
; #pragma unroll
;       for (int ks2 = 0; ks2 < 2; ++ks2) {
;         pf[qt][ks2].u[0] = pk2(pr[2 * ks2][0], pr[2 * ks2][1]);
;         pf[qt][ks2].u[1] = pk2(pr[2 * ks2][2], pr[2 * ks2][3]);
;         pf[qt][ks2].u[2] = pk2(pr[2 * ks2 + 1][0], pr[2 * ks2 + 1][1]);
;         pf[qt][ks2].u[3] = pk2(pr[2 * ks2 + 1][2], pr[2 * ks2 + 1][3]);
;       }
;     }
;   }
;   if (MODE != 0) {
; #pragma unroll
;     for (int ks2 = 0; ks2 < 2; ++ks2) {
; #pragma unroll
;       for (int dt = 0; dt < 4; ++dt) {
;         union { uint2 h[2]; bf16x8 v; } vf;
;         vf.h[0] = *(const uint2*)(sV + (16 * dt + l15) * 72 + 32 * ks2 + 4 * lg);
;         vf.h[1] = *(const uint2*)(sV + (16 * dt + l15) * 72 + 32 * ks2 + 16 + 4 * lg);
;         O[0][dt] = mfma16(vf.v, pf[0][ks2].v, O[0][dt]);
;         O[1][dt] = mfma16(vf.v, pf[1][ks2].v, O[1][dt]);
;       }
;     }
	v_max3_f32 v27, v24, v177, v178
	v_sub_f32_e32 v31, v26, v27
	v_exp_f32_e32 v31, v31
	v_sub_f32_e32 v172, v185, v27
	v_exp_f32_e32 v172, v172
	v_sub_f32_e32 v173, v187, v27
	v_cndmask_b32_e32 v26, 0, v31, vcc
	v_cmp_lt_f32_e32 vcc, s82, v185
	v_exp_f32_e32 v173, v173
	v_add_f32_e32 v31, 0, v26
	v_cndmask_b32_e32 v197, 0, v172, vcc
	v_sub_f32_e32 v172, v186, v27
	v_exp_f32_e32 v172, v172
	v_cmp_lt_f32_e32 vcc, s82, v186
	v_cvt_pk_bf16_f32 v111, v175, v176
	v_sub_f32_e32 v30, v24, v27
	v_cndmask_b32_e32 v198, 0, v172, vcc
	v_sub_f32_e32 v172, v112, v27
	v_cmp_lt_f32_e32 vcc, s82, v187
	v_exp_f32_e32 v172, v172
	v_cvt_pk_bf16_f32 v126, v181, v182
	v_cndmask_b32_e32 v199, 0, v173, vcc
	v_sub_f32_e32 v173, v113, v27
	v_exp_f32_e32 v173, v173
	v_cmp_lt_f32_e32 vcc, s82, v112
	v_sub_f32_e32 v112, v114, v27
	v_exp_f32_e32 v112, v112
	v_cndmask_b32_e32 v200, 0, v172, vcc
	v_cmp_lt_f32_e32 vcc, s82, v113
	v_sub_f32_e32 v113, v115, v27
	v_exp_f32_e32 v113, v113
	v_cndmask_b32_e32 v201, 0, v173, vcc
	v_cmp_lt_f32_e32 vcc, s82, v114
	v_cvt_pk_bf16_f32 v172, v26, v197
	v_add_u32_e32 v26, 0x2800, v180
	v_cndmask_b32_e32 v202, 0, v112, vcc
	v_sub_f32_e32 v112, v120, v27
	v_cmp_lt_f32_e32 vcc, s82, v115
	v_exp_f32_e32 v112, v112
	ds_read_b64 v[176:177], v26 offset:1280
	ds_read_b64 v[178:179], v26 offset:1312
	v_cndmask_b32_e32 v203, 0, v113, vcc
	v_sub_f32_e32 v113, v121, v27
	v_exp_f32_e32 v113, v113
	v_cmp_lt_f32_e32 vcc, s82, v120
	v_exp_f32_e32 v30, v30
	v_cvt_pk_bf16_f32 v127, v183, v184
	v_cndmask_b32_e32 v204, 0, v112, vcc
	v_sub_f32_e32 v112, v122, v27
	v_cmp_lt_f32_e32 vcc, s82, v121
	v_exp_f32_e32 v112, v112
	v_cvt_pk_bf16_f32 v173, v198, v199
	v_cndmask_b32_e32 v205, 0, v113, vcc
	v_sub_f32_e32 v113, v123, v27
	v_exp_f32_e32 v113, v113
	v_cmp_lt_f32_e32 vcc, s82, v122
	v_cvt_pk_bf16_f32 v174, v200, v201
	v_cvt_pk_bf16_f32 v175, v202, v203
	v_cndmask_b32_e32 v206, 0, v112, vcc
	v_sub_f32_e32 v112, v188, v27
	v_cmp_lt_f32_e32 vcc, s82, v123
	v_exp_f32_e32 v120, v112
	v_mul_f32_e32 v122, v66, v30
	v_mul_f32_e32 v123, v67, v30
	v_cndmask_b32_e32 v207, 0, v113, vcc
	ds_read_b64 v[112:113], v208 offset:1024
	ds_read_b64 v[114:115], v208 offset:1056
	v_cmp_lt_f32_e32 vcc, s82, v188
	v_add_u32_e32 v211, 0x3000, v180
	v_mul_f32_e32 v182, v58, v30
	v_mul_f32_e32 v183, v59, v30
	v_cndmask_b32_e32 v209, 0, v120, vcc
	v_sub_f32_e32 v120, v189, v27
	v_exp_f32_e32 v181, v120
	v_cmp_lt_f32_e32 vcc, s82, v189
	v_mul_f32_e32 v120, v64, v30
	v_mul_f32_e32 v121, v65, v30
	s_waitcnt lgkmcnt(0)
	v_mfma_f32_16x16x32_bf16 v[116:119], v[112:115], v[108:111], v[116:119]
	v_cndmask_b32_e32 v210, 0, v181, vcc
	v_mul_f32_e32 v180, v56, v30
	v_mul_f32_e32 v181, v57, v30
	v_sub_f32_e32 v188, v192, v27
	v_mfma_f32_16x16x32_bf16 v[112:115], v[112:115], v[172:175], v[120:123]
	v_exp_f32_e32 v193, v188
	v_cmp_lt_f32_e32 vcc, s82, v192
	s_nop 0
	ds_read_b64 v[120:121], v211 offset:1536
	ds_read_b64 v[122:123], v211 offset:1568
	v_mfma_f32_16x16x32_bf16 v[128:131], v[176:179], v[108:111], v[128:131]
	v_cndmask_b32_e32 v213, 0, v193, vcc
	v_cmp_lt_f32_e32 vcc, s82, v196
	v_mfma_f32_16x16x32_bf16 v[176:179], v[176:179], v[172:175], v[180:183]
	s_nop 2
	v_add3_u32 v180, s74, v133, v132
	v_add_u32_e32 v212, 0x2000, v180
	ds_read_b64 v[180:181], v212 offset:1024
	ds_read_b64 v[182:183], v212 offset:1056
	s_waitcnt lgkmcnt(1)
	v_mfma_f32_16x16x32_bf16 v[184:187], v[120:123], v[108:111], v[104:107]
	s_nop 2
	v_mul_f32_e64 v106, v50, v30
	v_mul_f32_e64 v107, v51, v30
	v_mul_f32_e32 v104, v48, v30
	v_mul_f32_e32 v105, v49, v30
	s_waitcnt lgkmcnt(0)
	v_mfma_f32_16x16x32_bf16 v[192:195], v[180:183], v[108:111], v[100:103]
	s_nop 2
	ds_read_b64 v[100:101], v208 offset:1088
	ds_read_b64 v[102:103], v208 offset:1120
	v_mfma_f32_16x16x32_bf16 v[188:191], v[120:123], v[172:175], v[104:107]
	s_nop 2
	v_sub_f32_e32 v104, v196, v27
	v_exp_f32_e32 v108, v104
	v_mul_f32_e32 v106, v42, v30
	v_mul_f32_e32 v107, v43, v30
	v_mul_f32_e32 v104, v40, v30
	v_mul_f32_e32 v105, v41, v30
	v_cndmask_b32_e32 v196, 0, v108, vcc
	ds_read_b64 v[108:109], v26 offset:1344
	ds_read_b64 v[110:111], v26 offset:1376
	v_add_f32_e32 v26, v197, v31
	v_add_f32_e32 v26, v198, v26
	v_add_f32_e32 v26, v199, v26
	v_add_f32_e32 v26, v200, v26
	v_add_f32_e32 v26, v201, v26
	v_mfma_f32_16x16x32_bf16 v[172:175], v[180:183], v[172:175], v[104:107]
	v_cvt_pk_bf16_f32 v180, v204, v205
	v_cvt_pk_bf16_f32 v181, v206, v207
	v_cvt_pk_bf16_f32 v182, v209, v210
	v_cvt_pk_bf16_f32 v183, v213, v196
	v_add_f32_e32 v26, v202, v26
	s_waitcnt lgkmcnt(1)
	v_mfma_f32_16x16x32_bf16 v[104:107], v[100:103], v[124:127], v[116:119]
	v_add_f32_e32 v26, v203, v26
	v_add_f32_e32 v26, v204, v26
	v_add_f32_e32 v26, v205, v26
	v_mfma_f32_16x16x32_bf16 v[100:103], v[100:103], v[180:183], v[112:115]
	ds_read_b64 v[116:117], v211 offset:1600
	ds_read_b64 v[118:119], v211 offset:1632
	v_add_f32_e32 v26, v206, v26
	v_add_f32_e32 v26, v207, v26
	s_waitcnt lgkmcnt(1)
	v_mfma_f32_16x16x32_bf16 v[112:115], v[108:111], v[124:127], v[128:131]
	v_add_f32_e32 v26, v209, v26
	v_add_f32_e32 v26, v210, v26
	v_add_f32_e32 v26, v213, v26
	v_mfma_f32_16x16x32_bf16 v[108:111], v[108:111], v[180:183], v[176:179]
	v_add_f32_e32 v26, v196, v26
	v_fmac_f32_e32 v26, v157, v30
	s_nop 0
	ds_read_b64 v[176:177], v212 offset:1088
	ds_read_b64 v[178:179], v212 offset:1120
	s_waitcnt lgkmcnt(1)
	v_mfma_f32_16x16x32_bf16 v[120:123], v[116:119], v[124:127], v[184:187]
	v_mfma_f32_16x16x32_bf16 v[116:119], v[116:119], v[180:183], v[188:191]
	s_waitcnt lgkmcnt(0)
	v_mfma_f32_16x16x32_bf16 v[128:131], v[176:179], v[124:127], v[192:195]
	v_mfma_f32_16x16x32_bf16 v[124:127], v[176:179], v[180:183], v[172:175]
	s_cbranch_execnz .LBB0_913
